# phase 6: merged bf16 tile through wave-private LDS transpose, 8 row-contiguous dwordx4 stores per wave instead of 128 short stores
# baseline (speedup 1.0000x reference)
.LBB0_2087:
	s_cmp_eq_u32 s5, 1
	s_mov_b32 s12, 0x7000000
	s_cselect_b32 s12, s12, 0x8800000
	s_cmp_lg_u32 s5, 0
	s_cselect_b32 s12, s12, 0x4800000
	v_mov_b32_e32 v0, 0
	s_add_u32 s12, s19, s12
	s_waitcnt vmcnt(8)
	v_mov_b32_e32 v49, v186
	s_addc_u32 s13, s20, 0
	s_add_u32 s22, s0, s8
	v_lshlrev_b32_e32 v16, 4, v49
	v_ashrrev_i32_e32 v50, 3, v49
	v_and_b32_e32 v48, 0x70, v16
	v_lshl_or_b32 v160, v50, 10, v48
	s_addc_u32 s23, s1, s9
	v_lshl_add_u64 v[32:33], s[22:23], 0, v[160:161]
	s_barrier
	global_load_dwordx4 v[16:19], v160, s[12:13]
	v_add_u32_e32 v148, 0x8000, v160
	v_mov_b32_e32 v149, v161
	v_add_co_u32_e32 v156, vcc, s94, v32
	global_load_dwordx4 v[20:23], v148, s[12:13]
	v_add_u32_e32 v152, 0x10000, v160
	v_addc_co_u32_e32 v157, vcc, 0, v33, vcc
	v_lshl_add_u64 v[36:37], s[22:23], 0, v[148:149]
	v_mov_b32_e32 v153, v161
	global_load_dwordx4 v[24:27], v152, s[12:13]
	v_add_u32_e32 v154, 0x18000, v160
	v_add_co_u32_e32 v158, vcc, s94, v36
	global_load_dwordx4 v[28:31], v154, s[12:13]
	s_nop 0
	v_addc_co_u32_e32 v159, vcc, 0, v37, vcc
	v_lshl_add_u64 v[40:41], s[22:23], 0, v[152:153]
	v_mov_b32_e32 v155, v161
	global_load_dwordx4 v[32:35], v[156:157], off
	v_add_co_u32_e32 v164, vcc, s94, v40
	global_load_dwordx4 v[36:39], v[158:159], off
	s_nop 0
	v_addc_co_u32_e32 v165, vcc, 0, v41, vcc
	v_lshl_add_u64 v[44:45], s[22:23], 0, v[154:155]
	global_load_dwordx4 v[40:43], v[164:165], off
	v_add_co_u32_e32 v166, vcc, s94, v44
	v_mad_u64_u32 v[146:147], s[22:23], v50, s43, v[48:49]
	s_nop 0
	v_addc_co_u32_e32 v167, vcc, 0, v45, vcc
	global_load_dwordx4 v[44:47], v[166:167], off
	global_load_dwordx4 v[80:83], v160, s[12:13] offset:128
	global_load_dwordx4 v[84:87], v148, s[12:13] offset:128
	global_load_dwordx4 v[88:91], v152, s[12:13] offset:128
	global_load_dwordx4 v[92:95], v154, s[12:13] offset:128
	global_load_dwordx4 v[64:67], v[156:157], off offset:128
	global_load_dwordx4 v[68:71], v[158:159], off offset:128
	global_load_dwordx4 v[72:75], v[164:165], off offset:128
	global_load_dwordx4 v[76:79], v[166:167], off offset:128
	v_mov_b32_e32 v1, v0
	v_mov_b32_e32 v2, v0
	v_mov_b32_e32 v3, v0
	v_mov_b32_e32 v4, v0
	v_mov_b32_e32 v5, v0
	v_mov_b32_e32 v6, v0
	v_mov_b32_e32 v7, v0
	s_waitcnt vmcnt(16)
	v_mov_b32_e32 v8, v0
	v_mov_b32_e32 v9, v0
	v_mov_b32_e32 v10, v0
	v_mov_b32_e32 v11, v0
	v_mov_b32_e32 v12, v0
	v_mov_b32_e32 v13, v0
	v_mov_b32_e32 v14, v0
	v_mov_b32_e32 v15, v0
	v_add_u32_e32 v149, 0xd800, v146
	s_waitcnt vmcnt(15)
	ds_write_b128 v146, v[16:19]
	s_waitcnt vmcnt(14)
	ds_write_b128 v146, v[20:23] offset:4608
	s_waitcnt vmcnt(13)
	ds_write_b128 v146, v[24:27] offset:9216
	s_waitcnt vmcnt(12)
	ds_write_b128 v146, v[28:31] offset:13824
	s_waitcnt vmcnt(11)
	ds_write_b128 v146, v[32:35] offset:36864
	s_waitcnt vmcnt(10)
	ds_write_b128 v146, v[36:39] offset:41472
	s_waitcnt vmcnt(9)
	ds_write_b128 v146, v[40:43] offset:46080
	s_waitcnt vmcnt(8)
	ds_write_b128 v146, v[44:47] offset:50688
	v_lshrrev_b32_e32 v18, 1, v49
	s_waitcnt lgkmcnt(0)
	s_barrier
	v_and_b32_e32 v17, 0x5f, v49
	v_and_b32_e32 v16, 16, v18
	global_load_dwordx4 v[112:115], v160, s[12:13] offset:256
	global_load_dwordx4 v[116:119], v148, s[12:13] offset:256
	global_load_dwordx4 v[120:123], v152, s[12:13] offset:256
	global_load_dwordx4 v[124:127], v154, s[12:13] offset:256
	global_load_dwordx4 v[96:99], v[156:157], off offset:256
	global_load_dwordx4 v[100:103], v[158:159], off offset:256
	global_load_dwordx4 v[104:107], v[164:165], off offset:256
	global_load_dwordx4 v[108:111], v[166:167], off offset:256
	v_mad_u32_u24 v147, v17, s43, v16
	v_and_b32_e32 v17, 31, v49
	v_and_or_b32 v17, v18, s44, v17
	v_mad_u64_u32 v[150:151], s[22:23], v17, s43, v[16:17]
	ds_read_b128 v[128:131], v150 offset:4608
	ds_read_b128 v[132:135], v147 offset:41472
	ds_read_b128 v[16:19], v150
	ds_read_b128 v[136:139], v150 offset:32
	ds_read_b128 v[140:143], v147 offset:36864
	ds_read_b128 v[200:203], v147 offset:36896
	s_waitcnt lgkmcnt(1)
	v_mfma_f32_32x32x16_bf16 v[48:63], v[16:19], v[140:143], v[0:15]
	v_mov_b32_e32 v151, v161
	v_mfma_f32_32x32x16_bf16 v[32:47], v[16:19], v[132:135], v[0:15]
	v_mfma_f32_32x32x16_bf16 v[16:31], v[128:131], v[140:143], v[0:15]
	v_mfma_f32_32x32x16_bf16 v[0:15], v[128:131], v[132:135], v[0:15]
	ds_read_b128 v[128:131], v150 offset:4640
	ds_read_b128 v[132:135], v147 offset:41504
	s_waitcnt vmcnt(15)
	ds_write_b128 v146, v[80:83] offset:18432
	s_waitcnt vmcnt(14)
	ds_write_b128 v146, v[84:87] offset:23040
	s_waitcnt vmcnt(13)
	ds_write_b128 v146, v[88:91] offset:27648
	s_waitcnt vmcnt(12)
	ds_write_b128 v146, v[92:95] offset:32256
	ds_read_b128 v[80:83], v150 offset:64
	ds_read_b128 v[84:87], v150 offset:4672
	ds_read_b128 v[88:91], v147 offset:36928
	ds_read_b128 v[92:95], v147 offset:41536
	s_waitcnt vmcnt(11)
	ds_write_b128 v146, v[64:67] offset:55296
	s_waitcnt vmcnt(10)
	ds_write_b128 v146, v[68:71] offset:59904
	s_waitcnt vmcnt(9)
	ds_write_b128 v146, v[72:75] offset:64512
	s_waitcnt vmcnt(8)
	ds_write_b128 v149, v[76:79] offset:13824
	ds_read_b128 v[64:67], v150 offset:96
	ds_read_b128 v[68:71], v150 offset:4704
	ds_read_b128 v[72:75], v147 offset:36960
	ds_read_b128 v[76:79], v147 offset:41568
	s_waitcnt lgkmcnt(0)
	s_barrier
	v_mfma_f32_32x32x16_bf16 v[48:63], v[136:139], v[200:203], v[48:63]
	v_mfma_f32_32x32x16_bf16 v[32:47], v[136:139], v[132:135], v[32:47]
	v_mfma_f32_32x32x16_bf16 v[16:31], v[128:131], v[200:203], v[16:31]
	v_mfma_f32_32x32x16_bf16 v[0:15], v[128:131], v[132:135], v[0:15]
	v_mfma_f32_32x32x16_bf16 v[48:63], v[80:83], v[88:91], v[48:63]
	v_mfma_f32_32x32x16_bf16 v[32:47], v[80:83], v[92:95], v[32:47]
	v_mfma_f32_32x32x16_bf16 v[16:31], v[84:87], v[88:91], v[16:31]
	v_mfma_f32_32x32x16_bf16 v[0:15], v[84:87], v[92:95], v[0:15]
	v_mfma_f32_32x32x16_bf16 v[48:63], v[64:67], v[72:75], v[48:63]
	v_mfma_f32_32x32x16_bf16 v[32:47], v[64:67], v[76:79], v[32:47]
	v_mfma_f32_32x32x16_bf16 v[16:31], v[68:71], v[72:75], v[16:31]
	v_mfma_f32_32x32x16_bf16 v[0:15], v[68:71], v[76:79], v[0:15]
	global_load_dwordx4 v[128:131], v160, s[12:13] offset:384
	global_load_dwordx4 v[132:135], v148, s[12:13] offset:384
	global_load_dwordx4 v[136:139], v152, s[12:13] offset:384
	global_load_dwordx4 v[140:143], v154, s[12:13] offset:384
	global_load_dwordx4 v[64:67], v[156:157], off offset:384
	global_load_dwordx4 v[68:71], v[158:159], off offset:384
	global_load_dwordx4 v[72:75], v[164:165], off offset:384
	global_load_dwordx4 v[76:79], v[166:167], off offset:384
	ds_read_b128 v[80:83], v150 offset:23040
	ds_read_b128 v[84:87], v147 offset:59904
	ds_read_b128 v[88:91], v150 offset:18432
	ds_read_b128 v[92:95], v150 offset:18464
	ds_read_b128 v[200:203], v147 offset:55296
	ds_read_b128 v[226:229], v147 offset:55328
	s_waitcnt lgkmcnt(1)
	v_mfma_f32_32x32x16_bf16 v[48:63], v[88:91], v[200:203], v[48:63]
	v_mfma_f32_32x32x16_bf16 v[32:47], v[88:91], v[84:87], v[32:47]
	v_mfma_f32_32x32x16_bf16 v[16:31], v[80:83], v[200:203], v[16:31]
	v_mfma_f32_32x32x16_bf16 v[0:15], v[80:83], v[84:87], v[0:15]
	ds_read_b128 v[80:83], v150 offset:23072
	ds_read_b128 v[84:87], v147 offset:59936
	s_waitcnt vmcnt(15)
	ds_write_b128 v146, v[112:115]
	s_waitcnt vmcnt(14)
	ds_write_b128 v146, v[116:119] offset:4608
	s_waitcnt vmcnt(13)
	ds_write_b128 v146, v[120:123] offset:9216
	s_waitcnt vmcnt(12)
	ds_write_b128 v146, v[124:127] offset:13824
	s_waitcnt lgkmcnt(6)
	v_mfma_f32_32x32x16_bf16 v[48:63], v[92:95], v[226:229], v[48:63]
	s_waitcnt lgkmcnt(4)
	v_mfma_f32_32x32x16_bf16 v[32:47], v[92:95], v[84:87], v[32:47]
	v_mfma_f32_32x32x16_bf16 v[16:31], v[80:83], v[226:229], v[16:31]
	v_mfma_f32_32x32x16_bf16 v[0:15], v[80:83], v[84:87], v[0:15]
	ds_read_b128 v[80:83], v150 offset:18496
	ds_read_b128 v[84:87], v150 offset:23104
	ds_read_b128 v[88:91], v147 offset:55360
	ds_read_b128 v[92:95], v147 offset:59968
	s_waitcnt vmcnt(11)
	ds_write_b128 v146, v[96:99] offset:36864
	s_waitcnt vmcnt(10)
	ds_write_b128 v146, v[100:103] offset:41472
	s_waitcnt vmcnt(9)
	ds_write_b128 v146, v[104:107] offset:46080
	s_waitcnt vmcnt(8)
	ds_write_b128 v146, v[108:111] offset:50688
	s_waitcnt lgkmcnt(5)
	v_mfma_f32_32x32x16_bf16 v[48:63], v[80:83], v[88:91], v[48:63]
	s_waitcnt lgkmcnt(4)
	v_mfma_f32_32x32x16_bf16 v[32:47], v[80:83], v[92:95], v[32:47]
	v_mfma_f32_32x32x16_bf16 v[16:31], v[84:87], v[88:91], v[16:31]
	v_mfma_f32_32x32x16_bf16 v[0:15], v[84:87], v[92:95], v[0:15]
	ds_read_b128 v[80:83], v150 offset:18528
	ds_read_b128 v[84:87], v150 offset:23136
	ds_read_b128 v[88:91], v147 offset:55392
	ds_read_b128 v[92:95], v147 offset:60000
	s_waitcnt lgkmcnt(0)
	s_barrier
	v_mfma_f32_32x32x16_bf16 v[48:63], v[80:83], v[88:91], v[48:63]
	v_mfma_f32_32x32x16_bf16 v[32:47], v[80:83], v[92:95], v[32:47]
	v_mfma_f32_32x32x16_bf16 v[16:31], v[84:87], v[88:91], v[16:31]
	v_mfma_f32_32x32x16_bf16 v[0:15], v[84:87], v[92:95], v[0:15]
	global_load_dwordx4 v[96:99], v160, s[12:13] offset:512
	global_load_dwordx4 v[100:103], v148, s[12:13] offset:512
	global_load_dwordx4 v[104:107], v152, s[12:13] offset:512
	global_load_dwordx4 v[108:111], v154, s[12:13] offset:512
	global_load_dwordx4 v[80:83], v[156:157], off offset:512
	global_load_dwordx4 v[84:87], v[158:159], off offset:512
	global_load_dwordx4 v[88:91], v[164:165], off offset:512
	global_load_dwordx4 v[92:95], v[166:167], off offset:512
	ds_read_b128 v[112:115], v150 offset:4608
	ds_read_b128 v[116:119], v147 offset:41472
	ds_read_b128 v[120:123], v150
	ds_read_b128 v[124:127], v150 offset:32
	ds_read_b128 v[200:203], v147 offset:36864
	ds_read_b128 v[226:229], v147 offset:36896
	s_waitcnt lgkmcnt(1)
	v_mfma_f32_32x32x16_bf16 v[48:63], v[120:123], v[200:203], v[48:63]
	v_mfma_f32_32x32x16_bf16 v[32:47], v[120:123], v[116:119], v[32:47]
	v_mfma_f32_32x32x16_bf16 v[16:31], v[112:115], v[200:203], v[16:31]
	v_mfma_f32_32x32x16_bf16 v[0:15], v[112:115], v[116:119], v[0:15]
	ds_read_b128 v[112:115], v150 offset:4640
	ds_read_b128 v[116:119], v147 offset:41504
	s_waitcnt vmcnt(15)
	ds_write_b128 v146, v[128:131] offset:18432
	s_waitcnt vmcnt(14)
	ds_write_b128 v146, v[132:135] offset:23040
	s_waitcnt vmcnt(13)
	ds_write_b128 v146, v[136:139] offset:27648
	s_waitcnt vmcnt(12)
	ds_write_b128 v146, v[140:143] offset:32256
	s_waitcnt lgkmcnt(6)
	v_mfma_f32_32x32x16_bf16 v[48:63], v[124:127], v[226:229], v[48:63]
	s_waitcnt lgkmcnt(4)
	v_mfma_f32_32x32x16_bf16 v[32:47], v[124:127], v[116:119], v[32:47]
	v_mfma_f32_32x32x16_bf16 v[16:31], v[112:115], v[226:229], v[16:31]
	v_mfma_f32_32x32x16_bf16 v[0:15], v[112:115], v[116:119], v[0:15]
	ds_read_b128 v[112:115], v150 offset:64
	ds_read_b128 v[116:119], v150 offset:4672
	ds_read_b128 v[120:123], v147 offset:36928
	ds_read_b128 v[124:127], v147 offset:41536
	s_waitcnt vmcnt(11)
	ds_write_b128 v146, v[64:67] offset:55296
	s_waitcnt vmcnt(10)
	ds_write_b128 v146, v[68:71] offset:59904
	s_waitcnt vmcnt(9)
	ds_write_b128 v146, v[72:75] offset:64512
	s_waitcnt vmcnt(8)
	ds_write_b128 v149, v[76:79] offset:13824
	ds_read_b128 v[64:67], v150 offset:96
	ds_read_b128 v[68:71], v150 offset:4704
	ds_read_b128 v[72:75], v147 offset:36960
	ds_read_b128 v[76:79], v147 offset:41568
	s_waitcnt lgkmcnt(0)
	s_barrier
	v_mfma_f32_32x32x16_bf16 v[48:63], v[112:115], v[120:123], v[48:63]
	v_mfma_f32_32x32x16_bf16 v[32:47], v[112:115], v[124:127], v[32:47]
	v_mfma_f32_32x32x16_bf16 v[16:31], v[116:119], v[120:123], v[16:31]
	v_mfma_f32_32x32x16_bf16 v[0:15], v[116:119], v[124:127], v[0:15]
	v_mfma_f32_32x32x16_bf16 v[48:63], v[64:67], v[72:75], v[48:63]
	v_mfma_f32_32x32x16_bf16 v[32:47], v[64:67], v[76:79], v[32:47]
	v_mfma_f32_32x32x16_bf16 v[16:31], v[68:71], v[72:75], v[16:31]
	v_mfma_f32_32x32x16_bf16 v[0:15], v[68:71], v[76:79], v[0:15]
	global_load_dwordx4 v[112:115], v160, s[12:13] offset:640
	global_load_dwordx4 v[116:119], v148, s[12:13] offset:640
	global_load_dwordx4 v[120:123], v152, s[12:13] offset:640
	global_load_dwordx4 v[124:127], v154, s[12:13] offset:640
	global_load_dwordx4 v[64:67], v[156:157], off offset:640
	global_load_dwordx4 v[68:71], v[158:159], off offset:640
	global_load_dwordx4 v[72:75], v[164:165], off offset:640
	global_load_dwordx4 v[76:79], v[166:167], off offset:640
	ds_read_b128 v[128:131], v150 offset:23040
	ds_read_b128 v[132:135], v147 offset:59904
	ds_read_b128 v[136:139], v150 offset:18432
	ds_read_b128 v[140:143], v150 offset:18464
	ds_read_b128 v[200:203], v147 offset:55296
	ds_read_b128 v[226:229], v147 offset:55328
	s_waitcnt lgkmcnt(1)
	v_mfma_f32_32x32x16_bf16 v[48:63], v[136:139], v[200:203], v[48:63]
	v_mfma_f32_32x32x16_bf16 v[32:47], v[136:139], v[132:135], v[32:47]
	v_mfma_f32_32x32x16_bf16 v[16:31], v[128:131], v[200:203], v[16:31]
	v_mfma_f32_32x32x16_bf16 v[0:15], v[128:131], v[132:135], v[0:15]
	ds_read_b128 v[128:131], v150 offset:23072
	ds_read_b128 v[132:135], v147 offset:59936
	s_waitcnt vmcnt(15)
	ds_write_b128 v146, v[96:99]
	s_waitcnt vmcnt(14)
	ds_write_b128 v146, v[100:103] offset:4608
	s_waitcnt vmcnt(13)
	ds_write_b128 v146, v[104:107] offset:9216
	s_waitcnt vmcnt(12)
	ds_write_b128 v146, v[108:111] offset:13824
	ds_read_b128 v[96:99], v150 offset:18496
	ds_read_b128 v[100:103], v150 offset:23104
	ds_read_b128 v[104:107], v147 offset:55360
	ds_read_b128 v[108:111], v147 offset:59968
	s_waitcnt vmcnt(11)
	ds_write_b128 v146, v[80:83] offset:36864
	s_waitcnt vmcnt(10)
	ds_write_b128 v146, v[84:87] offset:41472
	s_waitcnt vmcnt(9)
	ds_write_b128 v146, v[88:91] offset:46080
	s_waitcnt vmcnt(8)
	ds_write_b128 v146, v[92:95] offset:50688
	ds_read_b128 v[80:83], v150 offset:18528
	ds_read_b128 v[84:87], v150 offset:23136
	ds_read_b128 v[88:91], v147 offset:55392
	ds_read_b128 v[92:95], v147 offset:60000
	s_waitcnt lgkmcnt(0)
	s_barrier
	v_mfma_f32_32x32x16_bf16 v[48:63], v[140:143], v[226:229], v[48:63]
	v_mfma_f32_32x32x16_bf16 v[32:47], v[140:143], v[132:135], v[32:47]
	v_mfma_f32_32x32x16_bf16 v[16:31], v[128:131], v[226:229], v[16:31]
	v_mfma_f32_32x32x16_bf16 v[0:15], v[128:131], v[132:135], v[0:15]
	v_mfma_f32_32x32x16_bf16 v[48:63], v[96:99], v[104:107], v[48:63]
	v_mfma_f32_32x32x16_bf16 v[32:47], v[96:99], v[108:111], v[32:47]
	v_mfma_f32_32x32x16_bf16 v[16:31], v[100:103], v[104:107], v[16:31]
	v_mfma_f32_32x32x16_bf16 v[0:15], v[100:103], v[108:111], v[0:15]
	v_mfma_f32_32x32x16_bf16 v[48:63], v[80:83], v[88:91], v[48:63]
	v_mfma_f32_32x32x16_bf16 v[32:47], v[80:83], v[92:95], v[32:47]
	v_mfma_f32_32x32x16_bf16 v[16:31], v[84:87], v[88:91], v[16:31]
	v_mfma_f32_32x32x16_bf16 v[0:15], v[84:87], v[92:95], v[0:15]
	global_load_dwordx4 v[96:99], v160, s[12:13] offset:768
	global_load_dwordx4 v[100:103], v148, s[12:13] offset:768
	global_load_dwordx4 v[104:107], v152, s[12:13] offset:768
	global_load_dwordx4 v[108:111], v154, s[12:13] offset:768
	global_load_dwordx4 v[80:83], v[156:157], off offset:768
	global_load_dwordx4 v[84:87], v[158:159], off offset:768
	global_load_dwordx4 v[88:91], v[164:165], off offset:768
	global_load_dwordx4 v[92:95], v[166:167], off offset:768
	ds_read_b128 v[128:131], v150 offset:4608
	ds_read_b128 v[132:135], v147 offset:41472
	ds_read_b128 v[136:139], v150
	ds_read_b128 v[140:143], v150 offset:32
	ds_read_b128 v[200:203], v147 offset:36864
	ds_read_b128 v[226:229], v147 offset:36896
	s_waitcnt lgkmcnt(1)
	v_mfma_f32_32x32x16_bf16 v[48:63], v[136:139], v[200:203], v[48:63]
	v_mfma_f32_32x32x16_bf16 v[32:47], v[136:139], v[132:135], v[32:47]
	v_mfma_f32_32x32x16_bf16 v[16:31], v[128:131], v[200:203], v[16:31]
	v_mfma_f32_32x32x16_bf16 v[0:15], v[128:131], v[132:135], v[0:15]
	ds_read_b128 v[128:131], v150 offset:4640
	ds_read_b128 v[132:135], v147 offset:41504
	s_waitcnt vmcnt(15)
	ds_write_b128 v146, v[112:115] offset:18432
	s_waitcnt vmcnt(14)
	ds_write_b128 v146, v[116:119] offset:23040
	s_waitcnt vmcnt(13)
	ds_write_b128 v146, v[120:123] offset:27648
	s_waitcnt vmcnt(12)
	ds_write_b128 v146, v[124:127] offset:32256
	ds_read_b128 v[112:115], v150 offset:64
	ds_read_b128 v[116:119], v150 offset:4672
	ds_read_b128 v[120:123], v147 offset:36928
	ds_read_b128 v[124:127], v147 offset:41536
	s_waitcnt vmcnt(11)
	ds_write_b128 v146, v[64:67] offset:55296
	s_waitcnt vmcnt(10)
	ds_write_b128 v146, v[68:71] offset:59904
	s_waitcnt vmcnt(9)
	ds_write_b128 v146, v[72:75] offset:64512
	s_waitcnt vmcnt(8)
	ds_write_b128 v149, v[76:79] offset:13824
	ds_read_b128 v[64:67], v150 offset:96
	ds_read_b128 v[68:71], v150 offset:4704
	ds_read_b128 v[72:75], v147 offset:36960
	ds_read_b128 v[76:79], v147 offset:41568
	s_waitcnt lgkmcnt(0)
	s_barrier
	v_mfma_f32_32x32x16_bf16 v[48:63], v[140:143], v[226:229], v[48:63]
	v_mfma_f32_32x32x16_bf16 v[32:47], v[140:143], v[132:135], v[32:47]
	v_mfma_f32_32x32x16_bf16 v[16:31], v[128:131], v[226:229], v[16:31]
	v_mfma_f32_32x32x16_bf16 v[0:15], v[128:131], v[132:135], v[0:15]
	v_mfma_f32_32x32x16_bf16 v[48:63], v[112:115], v[120:123], v[48:63]
	v_mfma_f32_32x32x16_bf16 v[32:47], v[112:115], v[124:127], v[32:47]
	v_mfma_f32_32x32x16_bf16 v[16:31], v[116:119], v[120:123], v[16:31]
	v_mfma_f32_32x32x16_bf16 v[0:15], v[116:119], v[124:127], v[0:15]
	v_mfma_f32_32x32x16_bf16 v[48:63], v[64:67], v[72:75], v[48:63]
	v_mfma_f32_32x32x16_bf16 v[32:47], v[64:67], v[76:79], v[32:47]
	v_mfma_f32_32x32x16_bf16 v[16:31], v[68:71], v[72:75], v[16:31]
	v_mfma_f32_32x32x16_bf16 v[0:15], v[68:71], v[76:79], v[0:15]
	global_load_dwordx4 v[112:115], v160, s[12:13] offset:896
	global_load_dwordx4 v[116:119], v148, s[12:13] offset:896
	global_load_dwordx4 v[120:123], v152, s[12:13] offset:896
	global_load_dwordx4 v[124:127], v154, s[12:13] offset:896
	global_load_dwordx4 v[64:67], v[156:157], off offset:896
	global_load_dwordx4 v[68:71], v[158:159], off offset:896
	global_load_dwordx4 v[72:75], v[164:165], off offset:896
	global_load_dwordx4 v[76:79], v[166:167], off offset:896
	ds_read_b128 v[128:131], v150 offset:23040
	ds_read_b128 v[132:135], v147 offset:59904
	ds_read_b128 v[136:139], v150 offset:18432
	ds_read_b128 v[140:143], v150 offset:18464
	ds_read_b128 v[152:155], v147 offset:55296
	ds_read_b128 v[156:159], v147 offset:55328
	s_add_u32 s12, s0, s14
	s_addc_u32 s13, s1, s15
	s_add_i32 s5, s5, 1
	s_add_u32 s8, s8, 0x100000
	s_addc_u32 s9, s9, 0
	s_waitcnt lgkmcnt(1)
	v_mfma_f32_32x32x16_bf16 v[48:63], v[136:139], v[152:155], v[48:63]
	s_add_u32 s14, s14, 0x200000
	s_addc_u32 s15, s15, 0
	s_cmp_eq_u32 s5, 3
	v_mfma_f32_32x32x16_bf16 v[0:15], v[128:131], v[132:135], v[0:15]
	v_mfma_f32_32x32x16_bf16 v[16:31], v[128:131], v[152:155], v[16:31]
	v_mov_b32_e32 v153, v161
	v_mfma_f32_32x32x16_bf16 v[32:47], v[136:139], v[132:135], v[32:47]
	ds_read_b128 v[128:131], v150 offset:23072
	ds_read_b128 v[132:135], v147 offset:59936
	s_waitcnt vmcnt(15)
	ds_write_b128 v146, v[96:99]
	s_waitcnt vmcnt(14)
	ds_write_b128 v146, v[100:103] offset:4608
	s_waitcnt vmcnt(13)
	ds_write_b128 v146, v[104:107] offset:9216
	s_waitcnt vmcnt(12)
	ds_write_b128 v146, v[108:111] offset:13824
	ds_read_b128 v[96:99], v150 offset:18496
	ds_read_b128 v[100:103], v150 offset:23104
	ds_read_b128 v[104:107], v147 offset:55360
	ds_read_b128 v[108:111], v147 offset:59968
	s_waitcnt vmcnt(11)
	ds_write_b128 v146, v[80:83] offset:36864
	s_waitcnt vmcnt(10)
	ds_write_b128 v146, v[84:87] offset:41472
	s_waitcnt vmcnt(9)
	ds_write_b128 v146, v[88:91] offset:46080
	s_waitcnt vmcnt(8)
	ds_write_b128 v146, v[92:95] offset:50688
	ds_read_b128 v[80:83], v150 offset:18528
	ds_read_b128 v[84:87], v150 offset:23136
	ds_read_b128 v[88:91], v147 offset:55392
	ds_read_b128 v[92:95], v147 offset:60000
	s_waitcnt lgkmcnt(0)
	s_barrier
	v_mfma_f32_32x32x16_bf16 v[48:63], v[140:143], v[156:159], v[48:63]
	v_mfma_f32_32x32x16_bf16 v[0:15], v[128:131], v[132:135], v[0:15]
	v_mfma_f32_32x32x16_bf16 v[16:31], v[128:131], v[156:159], v[16:31]
	v_mfma_f32_32x32x16_bf16 v[32:47], v[140:143], v[132:135], v[32:47]
	v_mfma_f32_32x32x16_bf16 v[48:63], v[96:99], v[104:107], v[48:63]
	v_mfma_f32_32x32x16_bf16 v[0:15], v[100:103], v[108:111], v[0:15]
	v_mfma_f32_32x32x16_bf16 v[16:31], v[100:103], v[104:107], v[16:31]
	v_mfma_f32_32x32x16_bf16 v[32:47], v[96:99], v[108:111], v[32:47]
	v_mfma_f32_32x32x16_bf16 v[48:63], v[80:83], v[88:91], v[48:63]
	v_mfma_f32_32x32x16_bf16 v[0:15], v[84:87], v[92:95], v[0:15]
	v_mfma_f32_32x32x16_bf16 v[16:31], v[84:87], v[88:91], v[16:31]
	v_mfma_f32_32x32x16_bf16 v[32:47], v[80:83], v[92:95], v[32:47]
	ds_read_b128 v[80:83], v150 offset:4608
	ds_read_b128 v[84:87], v147 offset:41472
	ds_read_b128 v[88:91], v150
	ds_read_b128 v[92:95], v150 offset:32
	ds_read_b128 v[96:99], v147 offset:36864
	ds_read_b128 v[100:103], v147 offset:36896
	s_waitcnt lgkmcnt(1)
	v_mfma_f32_32x32x16_bf16 v[48:63], v[88:91], v[96:99], v[48:63]
	v_mfma_f32_32x32x16_bf16 v[0:15], v[80:83], v[84:87], v[0:15]
	v_mfma_f32_32x32x16_bf16 v[16:31], v[80:83], v[96:99], v[16:31]
	v_mfma_f32_32x32x16_bf16 v[32:47], v[88:91], v[84:87], v[32:47]
	ds_read_b128 v[80:83], v150 offset:4640
	ds_read_b128 v[84:87], v147 offset:41504
	s_waitcnt vmcnt(7)
	ds_write_b128 v146, v[112:115] offset:18432
	s_waitcnt vmcnt(6)
	ds_write_b128 v146, v[116:119] offset:23040
	s_waitcnt vmcnt(5)
	ds_write_b128 v146, v[120:123] offset:27648
	s_waitcnt vmcnt(4)
	ds_write_b128 v146, v[124:127] offset:32256
	s_waitcnt lgkmcnt(6)
	v_mfma_f32_32x32x16_bf16 v[48:63], v[92:95], v[100:103], v[48:63]
	s_waitcnt lgkmcnt(4)
	v_mfma_f32_32x32x16_bf16 v[0:15], v[80:83], v[84:87], v[0:15]
	v_mfma_f32_32x32x16_bf16 v[16:31], v[80:83], v[100:103], v[16:31]
	v_mfma_f32_32x32x16_bf16 v[32:47], v[92:95], v[84:87], v[32:47]
	ds_read_b128 v[80:83], v150 offset:64
	ds_read_b128 v[84:87], v150 offset:4672
	ds_read_b128 v[88:91], v147 offset:36928
	ds_read_b128 v[92:95], v147 offset:41536
	s_waitcnt vmcnt(3)
	ds_write_b128 v146, v[64:67] offset:55296
	s_waitcnt vmcnt(2)
	ds_write_b128 v146, v[68:71] offset:59904
	s_waitcnt vmcnt(1)
	ds_write_b128 v146, v[72:75] offset:64512
	s_waitcnt vmcnt(0)
	ds_write_b128 v149, v[76:79] offset:13824
	ds_read_b128 v[64:67], v150 offset:96
	ds_read_b128 v[68:71], v150 offset:4704
	ds_read_b128 v[72:75], v147 offset:36960
	ds_read_b128 v[76:79], v147 offset:41568
	s_waitcnt lgkmcnt(0)
	s_barrier
	v_mov_b32_e32 v149, v161
	v_mfma_f32_32x32x16_bf16 v[48:63], v[80:83], v[88:91], v[48:63]
	v_mfma_f32_32x32x16_bf16 v[0:15], v[84:87], v[92:95], v[0:15]
	v_mfma_f32_32x32x16_bf16 v[16:31], v[84:87], v[88:91], v[16:31]
	v_mfma_f32_32x32x16_bf16 v[32:47], v[80:83], v[92:95], v[32:47]
	v_mfma_f32_32x32x16_bf16 v[48:63], v[64:67], v[72:75], v[48:63]
	v_mfma_f32_32x32x16_bf16 v[0:15], v[68:71], v[76:79], v[0:15]
	v_mfma_f32_32x32x16_bf16 v[16:31], v[68:71], v[72:75], v[16:31]
	v_mfma_f32_32x32x16_bf16 v[32:47], v[64:67], v[76:79], v[32:47]
	ds_read_b128 v[64:67], v150 offset:23040
	ds_read_b128 v[68:71], v147 offset:59904
	ds_read_b128 v[72:75], v150 offset:18432
	ds_read_b128 v[76:79], v150 offset:18464
	ds_read_b128 v[80:83], v147 offset:55296
	ds_read_b128 v[84:87], v147 offset:55328
	s_waitcnt lgkmcnt(1)
	v_mfma_f32_32x32x16_bf16 v[48:63], v[72:75], v[80:83], v[48:63]
	v_mfma_f32_32x32x16_bf16 v[0:15], v[64:67], v[68:71], v[0:15]
	v_mfma_f32_32x32x16_bf16 v[16:31], v[64:67], v[80:83], v[16:31]
	v_mfma_f32_32x32x16_bf16 v[32:47], v[72:75], v[68:71], v[32:47]
	ds_read_b128 v[64:67], v150 offset:23072
	ds_read_b128 v[68:71], v147 offset:59936
	s_waitcnt lgkmcnt(2)
	v_mfma_f32_32x32x16_bf16 v[48:63], v[76:79], v[84:87], v[48:63]
	s_waitcnt lgkmcnt(0)
	v_mfma_f32_32x32x16_bf16 v[0:15], v[64:67], v[68:71], v[0:15]
	v_mfma_f32_32x32x16_bf16 v[16:31], v[64:67], v[84:87], v[16:31]
	v_mfma_f32_32x32x16_bf16 v[32:47], v[76:79], v[68:71], v[32:47]
	ds_read_b128 v[64:67], v147 offset:59968
	ds_read_b128 v[68:71], v147 offset:55360
	ds_read_b128 v[72:75], v150 offset:23104
	ds_read_b128 v[76:79], v150 offset:18496
	s_waitcnt lgkmcnt(0)
	v_mfma_f32_32x32x16_bf16 v[48:63], v[76:79], v[68:71], v[48:63]
	v_mfma_f32_32x32x16_bf16 v[0:15], v[72:75], v[64:67], v[0:15]
	v_mfma_f32_32x32x16_bf16 v[16:31], v[72:75], v[68:71], v[16:31]
	v_mfma_f32_32x32x16_bf16 v[32:47], v[76:79], v[64:67], v[32:47]
	ds_read_b128 v[64:67], v147 offset:60000
	ds_read_b128 v[68:71], v147 offset:55392
	ds_read_b128 v[72:75], v150 offset:23136
	ds_read_b128 v[76:79], v150 offset:18528
	s_waitcnt lgkmcnt(0)
	s_barrier
	v_mfma_f32_32x32x16_bf16 v[48:63], v[76:79], v[68:71], v[48:63]
	v_mfma_f32_32x32x16_bf16 v[0:15], v[72:75], v[64:67], v[0:15]
	s_nop 10
	v_cvt_pk_bf16_f32 v200, v48, v49
	v_mov_b32_e32 v49, v186
	v_cvt_pk_bf16_f32 v189, v50, v51
	v_cvt_pk_bf16_f32 v188, v52, v53
	v_cvt_pk_bf16_f32 v208, v54, v55
	v_cvt_pk_bf16_f32 v195, v56, v57
	v_cvt_pk_bf16_f32 v192, v58, v59
	v_mfma_f32_32x32x16_bf16 v[16:31], v[72:75], v[68:71], v[16:31]
	v_cvt_pk_bf16_f32 v232, v0, v1
	v_mov_b32_e32 v0, v161
	s_nop 0
	v_ashrrev_i32_e32 v50, 3, v49
	s_barrier
	v_mfma_f32_32x32x16_bf16 v[32:47], v[76:79], v[64:67], v[32:47]
	s_nop 5
	v_cvt_pk_bf16_f32 v240, v16, v17
	v_lshlrev_b32_e32 v16, 4, v49
	v_and_b32_e32 v48, 0x70, v16
	v_lshl_or_b32 v160, v50, 11, v48
	v_cvt_pk_bf16_f32 v239, v18, v19
	global_load_dwordx4 v[16:19], v160, s[10:11]
	v_cvt_pk_bf16_f32 v248, v32, v33
	v_lshl_add_u64 v[32:33], s[12:13], 0, v[160:161]
	v_add_u32_e32 v148, 0x10000, v160
	v_add_co_u32_e32 v154, vcc, s95, v32
	v_cvt_pk_bf16_f32 v246, v36, v37
	v_cvt_pk_bf16_f32 v238, v20, v21
	v_cvt_pk_bf16_f32 v237, v22, v23
	global_load_dwordx4 v[20:23], v148, s[10:11]
	v_add_u32_e32 v150, 0x20000, v160
	v_addc_co_u32_e32 v155, vcc, 0, v33, vcc
	v_lshl_add_u64 v[36:37], s[12:13], 0, v[148:149]
	v_cvt_pk_bf16_f32 v236, v24, v25
	v_cvt_pk_bf16_f32 v235, v26, v27
	global_load_dwordx4 v[24:27], v150, s[10:11]
	v_add_u32_e32 v152, 0x30000, v160
	v_add_co_u32_e32 v156, vcc, s95, v36
	v_cvt_pk_bf16_f32 v244, v40, v41
	v_cvt_pk_bf16_f32 v234, v28, v29
	v_cvt_pk_bf16_f32 v233, v30, v31
	global_load_dwordx4 v[28:31], v152, s[10:11]
	v_addc_co_u32_e32 v157, vcc, 0, v37, vcc
	v_lshl_add_u64 v[40:41], s[12:13], 0, v[150:151]
	v_cvt_pk_bf16_f32 v247, v34, v35
	global_load_dwordx4 v[32:35], v[154:155], off
	v_add_co_u32_e32 v158, vcc, s95, v40
	v_cvt_pk_bf16_f32 v245, v38, v39
	v_cvt_pk_bf16_f32 v242, v44, v45
	global_load_dwordx4 v[36:39], v[156:157], off
	v_addc_co_u32_e32 v159, vcc, 0, v41, vcc
	v_lshl_add_u64 v[44:45], s[12:13], 0, v[152:153]
	v_cvt_pk_bf16_f32 v243, v42, v43
	global_load_dwordx4 v[40:43], v[158:159], off
	v_add_co_u32_e32 v164, vcc, s95, v44
	v_cvt_pk_bf16_f32 v241, v46, v47
	s_nop 0
	v_addc_co_u32_e32 v165, vcc, 0, v45, vcc
	global_load_dwordx4 v[44:47], v[164:165], off
	global_load_dwordx4 v[80:83], v160, s[10:11] offset:128
	global_load_dwordx4 v[84:87], v148, s[10:11] offset:128
	global_load_dwordx4 v[88:91], v150, s[10:11] offset:128
	global_load_dwordx4 v[92:95], v152, s[10:11] offset:128
	global_load_dwordx4 v[64:67], v[154:155], off offset:128
	global_load_dwordx4 v[68:71], v[156:157], off offset:128
	global_load_dwordx4 v[72:75], v[158:159], off offset:128
	global_load_dwordx4 v[76:79], v[164:165], off offset:128
	v_mad_u64_u32 v[146:147], s[12:13], v50, s43, v[48:49]
	s_waitcnt vmcnt(15)
	ds_write_b128 v146, v[16:19]
	s_waitcnt vmcnt(14)
	ds_write_b128 v146, v[20:23] offset:4608
	s_waitcnt vmcnt(13)
	ds_write_b128 v146, v[24:27] offset:9216
	s_waitcnt vmcnt(12)
	ds_write_b128 v146, v[28:31] offset:13824
	s_waitcnt vmcnt(11)
	ds_write_b128 v146, v[32:35] offset:36864
	s_waitcnt vmcnt(10)
	ds_write_b128 v146, v[36:39] offset:41472
	s_waitcnt vmcnt(9)
	ds_write_b128 v146, v[40:43] offset:46080
	s_waitcnt vmcnt(8)
	ds_write_b128 v146, v[44:47] offset:50688
	v_lshrrev_b32_e32 v18, 1, v49
	s_waitcnt lgkmcnt(0)
	s_barrier
	v_and_b32_e32 v17, 0x5f, v49
	v_and_b32_e32 v16, 16, v18
	global_load_dwordx4 v[112:115], v160, s[10:11] offset:256
	global_load_dwordx4 v[116:119], v148, s[10:11] offset:256
	global_load_dwordx4 v[120:123], v150, s[10:11] offset:256
	global_load_dwordx4 v[124:127], v152, s[10:11] offset:256
	global_load_dwordx4 v[96:99], v[154:155], off offset:256
	global_load_dwordx4 v[100:103], v[156:157], off offset:256
	global_load_dwordx4 v[104:107], v[158:159], off offset:256
	global_load_dwordx4 v[108:111], v[164:165], off offset:256
	v_mad_u32_u24 v147, v17, s43, v16
	v_and_b32_e32 v17, 31, v49
	v_and_or_b32 v17, v18, s44, v17
	v_mad_u64_u32 v[166:167], s[12:13], v17, s43, v[16:17]
	ds_read_b128 v[128:131], v166 offset:4608
	ds_read_b128 v[132:135], v147 offset:41472
	ds_read_b128 v[16:19], v166
	ds_read_b128 v[136:139], v166 offset:32
	ds_read_b128 v[140:143], v147 offset:36864
	ds_read_b128 v[202:205], v147 offset:36896
	v_cvt_pk_bf16_f32 v231, v2, v3
	v_cvt_pk_bf16_f32 v230, v4, v5
	v_cvt_pk_bf16_f32 v229, v6, v7
	v_cvt_pk_bf16_f32 v228, v8, v9
	v_cvt_pk_bf16_f32 v227, v10, v11
	v_cvt_pk_bf16_f32 v226, v12, v13
	v_cvt_pk_bf16_f32 v225, v14, v15
	v_mov_b32_e32 v1, v0
	v_mov_b32_e32 v2, v0
	v_mov_b32_e32 v3, v0
	v_mov_b32_e32 v4, v0
	v_mov_b32_e32 v5, v0
	v_mov_b32_e32 v6, v0
	v_mov_b32_e32 v7, v0
	v_mov_b32_e32 v8, v0
	v_mov_b32_e32 v9, v0
	v_mov_b32_e32 v10, v0
	v_mov_b32_e32 v11, v0
	v_mov_b32_e32 v12, v0
	v_mov_b32_e32 v13, v0
	v_mov_b32_e32 v14, v0
	v_mov_b32_e32 v15, v0
	v_cvt_pk_bf16_f32 v250, v60, v61
	v_cvt_pk_bf16_f32 v249, v62, v63
	s_waitcnt lgkmcnt(1)
	v_mfma_f32_32x32x16_bf16 v[48:63], v[16:19], v[140:143], v[0:15]
	v_add_u32_e32 v149, 0xd800, v146
	v_mfma_f32_32x32x16_bf16 v[32:47], v[16:19], v[132:135], v[0:15]
	v_mfma_f32_32x32x16_bf16 v[16:31], v[128:131], v[140:143], v[0:15]
	v_mfma_f32_32x32x16_bf16 v[0:15], v[128:131], v[132:135], v[0:15]
	ds_read_b128 v[128:131], v166 offset:4640
	ds_read_b128 v[132:135], v147 offset:41504
	s_waitcnt vmcnt(15)
	ds_write_b128 v146, v[80:83] offset:18432
	s_waitcnt vmcnt(14)
	ds_write_b128 v146, v[84:87] offset:23040
	s_waitcnt vmcnt(13)
	ds_write_b128 v146, v[88:91] offset:27648
	s_waitcnt vmcnt(12)
	ds_write_b128 v146, v[92:95] offset:32256
	ds_read_b128 v[80:83], v166 offset:64
	ds_read_b128 v[84:87], v166 offset:4672
	ds_read_b128 v[88:91], v147 offset:36928
	ds_read_b128 v[92:95], v147 offset:41536
	s_waitcnt vmcnt(11)
	ds_write_b128 v146, v[64:67] offset:55296
	s_waitcnt vmcnt(10)
	ds_write_b128 v146, v[68:71] offset:59904
	s_waitcnt vmcnt(9)
	ds_write_b128 v146, v[72:75] offset:64512
	s_waitcnt vmcnt(8)
	ds_write_b128 v149, v[76:79] offset:13824
	ds_read_b128 v[64:67], v166 offset:96
	ds_read_b128 v[68:71], v166 offset:4704
	ds_read_b128 v[72:75], v147 offset:36960
	ds_read_b128 v[76:79], v147 offset:41568
	s_waitcnt lgkmcnt(0)
	s_barrier
	v_mfma_f32_32x32x16_bf16 v[48:63], v[136:139], v[202:205], v[48:63]
	v_mfma_f32_32x32x16_bf16 v[32:47], v[136:139], v[132:135], v[32:47]
	v_mfma_f32_32x32x16_bf16 v[16:31], v[128:131], v[202:205], v[16:31]
	v_mfma_f32_32x32x16_bf16 v[0:15], v[128:131], v[132:135], v[0:15]
	v_mfma_f32_32x32x16_bf16 v[48:63], v[80:83], v[88:91], v[48:63]
	v_mfma_f32_32x32x16_bf16 v[32:47], v[80:83], v[92:95], v[32:47]
	v_mfma_f32_32x32x16_bf16 v[16:31], v[84:87], v[88:91], v[16:31]
	v_mfma_f32_32x32x16_bf16 v[0:15], v[84:87], v[92:95], v[0:15]
	v_mfma_f32_32x32x16_bf16 v[48:63], v[64:67], v[72:75], v[48:63]
	v_mfma_f32_32x32x16_bf16 v[32:47], v[64:67], v[76:79], v[32:47]
	v_mfma_f32_32x32x16_bf16 v[16:31], v[68:71], v[72:75], v[16:31]
	v_mfma_f32_32x32x16_bf16 v[0:15], v[68:71], v[76:79], v[0:15]
	global_load_dwordx4 v[128:131], v160, s[10:11] offset:384
	global_load_dwordx4 v[132:135], v148, s[10:11] offset:384
	global_load_dwordx4 v[136:139], v150, s[10:11] offset:384
	global_load_dwordx4 v[140:143], v152, s[10:11] offset:384
	global_load_dwordx4 v[64:67], v[154:155], off offset:384
	global_load_dwordx4 v[68:71], v[156:157], off offset:384
	global_load_dwordx4 v[72:75], v[158:159], off offset:384
	global_load_dwordx4 v[76:79], v[164:165], off offset:384
	ds_read_b128 v[80:83], v166 offset:23040
	ds_read_b128 v[84:87], v147 offset:59904
	ds_read_b128 v[88:91], v166 offset:18432
	ds_read_b128 v[92:95], v166 offset:18464
	ds_read_b128 v[202:205], v147 offset:55296
	ds_read_b128 v[196:199], v147 offset:55328
	s_waitcnt lgkmcnt(1)
	v_mfma_f32_32x32x16_bf16 v[48:63], v[88:91], v[202:205], v[48:63]
	v_mfma_f32_32x32x16_bf16 v[32:47], v[88:91], v[84:87], v[32:47]
	v_mfma_f32_32x32x16_bf16 v[16:31], v[80:83], v[202:205], v[16:31]
	v_mfma_f32_32x32x16_bf16 v[0:15], v[80:83], v[84:87], v[0:15]
	ds_read_b128 v[80:83], v166 offset:23072
	ds_read_b128 v[84:87], v147 offset:59936
	s_waitcnt vmcnt(15)
	ds_write_b128 v146, v[112:115]
	s_waitcnt vmcnt(14)
	ds_write_b128 v146, v[116:119] offset:4608
	s_waitcnt vmcnt(13)
	ds_write_b128 v146, v[120:123] offset:9216
	s_waitcnt vmcnt(12)
	ds_write_b128 v146, v[124:127] offset:13824
	s_waitcnt lgkmcnt(6)
	v_mfma_f32_32x32x16_bf16 v[48:63], v[92:95], v[196:199], v[48:63]
	s_waitcnt lgkmcnt(4)
	v_mfma_f32_32x32x16_bf16 v[32:47], v[92:95], v[84:87], v[32:47]
	v_mfma_f32_32x32x16_bf16 v[16:31], v[80:83], v[196:199], v[16:31]
	v_mfma_f32_32x32x16_bf16 v[0:15], v[80:83], v[84:87], v[0:15]
	ds_read_b128 v[80:83], v166 offset:18496
	ds_read_b128 v[84:87], v166 offset:23104
	ds_read_b128 v[88:91], v147 offset:55360
	ds_read_b128 v[92:95], v147 offset:59968
	s_waitcnt vmcnt(11)
	ds_write_b128 v146, v[96:99] offset:36864
	s_waitcnt vmcnt(10)
	ds_write_b128 v146, v[100:103] offset:41472
	s_waitcnt vmcnt(9)
	ds_write_b128 v146, v[104:107] offset:46080
	s_waitcnt vmcnt(8)
	ds_write_b128 v146, v[108:111] offset:50688
	s_waitcnt lgkmcnt(5)
	v_mfma_f32_32x32x16_bf16 v[48:63], v[80:83], v[88:91], v[48:63]
	s_waitcnt lgkmcnt(4)
	v_mfma_f32_32x32x16_bf16 v[32:47], v[80:83], v[92:95], v[32:47]
	v_mfma_f32_32x32x16_bf16 v[16:31], v[84:87], v[88:91], v[16:31]
	v_mfma_f32_32x32x16_bf16 v[0:15], v[84:87], v[92:95], v[0:15]
	ds_read_b128 v[80:83], v166 offset:18528
	ds_read_b128 v[84:87], v166 offset:23136
	ds_read_b128 v[88:91], v147 offset:55392
	ds_read_b128 v[92:95], v147 offset:60000
	s_waitcnt lgkmcnt(0)
	s_barrier
	v_mfma_f32_32x32x16_bf16 v[48:63], v[80:83], v[88:91], v[48:63]
	v_mfma_f32_32x32x16_bf16 v[32:47], v[80:83], v[92:95], v[32:47]
	v_mfma_f32_32x32x16_bf16 v[16:31], v[84:87], v[88:91], v[16:31]
	v_mfma_f32_32x32x16_bf16 v[0:15], v[84:87], v[92:95], v[0:15]
	global_load_dwordx4 v[96:99], v160, s[10:11] offset:512
	global_load_dwordx4 v[100:103], v148, s[10:11] offset:512
	global_load_dwordx4 v[104:107], v150, s[10:11] offset:512
	global_load_dwordx4 v[108:111], v152, s[10:11] offset:512
	global_load_dwordx4 v[80:83], v[154:155], off offset:512
	global_load_dwordx4 v[84:87], v[156:157], off offset:512
	global_load_dwordx4 v[88:91], v[158:159], off offset:512
	global_load_dwordx4 v[92:95], v[164:165], off offset:512
	ds_read_b128 v[112:115], v166 offset:4608
	ds_read_b128 v[116:119], v147 offset:41472
	ds_read_b128 v[120:123], v166
	ds_read_b128 v[124:127], v166 offset:32
	ds_read_b128 v[196:199], v147 offset:36864
	ds_read_b128 v[202:205], v147 offset:36896
	s_waitcnt lgkmcnt(1)
	v_mfma_f32_32x32x16_bf16 v[48:63], v[120:123], v[196:199], v[48:63]
	v_mfma_f32_32x32x16_bf16 v[32:47], v[120:123], v[116:119], v[32:47]
	v_mfma_f32_32x32x16_bf16 v[16:31], v[112:115], v[196:199], v[16:31]
	v_mfma_f32_32x32x16_bf16 v[0:15], v[112:115], v[116:119], v[0:15]
	ds_read_b128 v[112:115], v166 offset:4640
	ds_read_b128 v[116:119], v147 offset:41504
	s_waitcnt vmcnt(15)
	ds_write_b128 v146, v[128:131] offset:18432
	s_waitcnt vmcnt(14)
	ds_write_b128 v146, v[132:135] offset:23040
	s_waitcnt vmcnt(13)
	ds_write_b128 v146, v[136:139] offset:27648
	s_waitcnt vmcnt(12)
	ds_write_b128 v146, v[140:143] offset:32256
	s_waitcnt lgkmcnt(6)
	v_mfma_f32_32x32x16_bf16 v[48:63], v[124:127], v[202:205], v[48:63]
	s_waitcnt lgkmcnt(4)
	v_mfma_f32_32x32x16_bf16 v[32:47], v[124:127], v[116:119], v[32:47]
	v_mfma_f32_32x32x16_bf16 v[16:31], v[112:115], v[202:205], v[16:31]
	v_mfma_f32_32x32x16_bf16 v[0:15], v[112:115], v[116:119], v[0:15]
	ds_read_b128 v[112:115], v166 offset:64
	ds_read_b128 v[116:119], v166 offset:4672
	ds_read_b128 v[120:123], v147 offset:36928
	ds_read_b128 v[124:127], v147 offset:41536
	s_waitcnt vmcnt(11)
	ds_write_b128 v146, v[64:67] offset:55296
	s_waitcnt vmcnt(10)
	ds_write_b128 v146, v[68:71] offset:59904
	s_waitcnt vmcnt(9)
	ds_write_b128 v146, v[72:75] offset:64512
	s_waitcnt vmcnt(8)
	ds_write_b128 v149, v[76:79] offset:13824
	ds_read_b128 v[64:67], v166 offset:96
	ds_read_b128 v[68:71], v166 offset:4704
	ds_read_b128 v[72:75], v147 offset:36960
	ds_read_b128 v[76:79], v147 offset:41568
	s_waitcnt lgkmcnt(0)
	s_barrier
	v_mfma_f32_32x32x16_bf16 v[48:63], v[112:115], v[120:123], v[48:63]
	v_mfma_f32_32x32x16_bf16 v[32:47], v[112:115], v[124:127], v[32:47]
	v_mfma_f32_32x32x16_bf16 v[16:31], v[116:119], v[120:123], v[16:31]
	v_mfma_f32_32x32x16_bf16 v[0:15], v[116:119], v[124:127], v[0:15]
	v_mfma_f32_32x32x16_bf16 v[48:63], v[64:67], v[72:75], v[48:63]
	v_mfma_f32_32x32x16_bf16 v[32:47], v[64:67], v[76:79], v[32:47]
	v_mfma_f32_32x32x16_bf16 v[16:31], v[68:71], v[72:75], v[16:31]
	v_mfma_f32_32x32x16_bf16 v[0:15], v[68:71], v[76:79], v[0:15]
	global_load_dwordx4 v[112:115], v160, s[10:11] offset:640
	global_load_dwordx4 v[116:119], v148, s[10:11] offset:640
	global_load_dwordx4 v[120:123], v150, s[10:11] offset:640
	global_load_dwordx4 v[124:127], v152, s[10:11] offset:640
	global_load_dwordx4 v[64:67], v[154:155], off offset:640
	global_load_dwordx4 v[68:71], v[156:157], off offset:640
	global_load_dwordx4 v[72:75], v[158:159], off offset:640
	global_load_dwordx4 v[76:79], v[164:165], off offset:640
	ds_read_b128 v[128:131], v166 offset:23040
	ds_read_b128 v[132:135], v147 offset:59904
	ds_read_b128 v[136:139], v166 offset:18432
	ds_read_b128 v[140:143], v166 offset:18464
	ds_read_b128 v[196:199], v147 offset:55296
	ds_read_b128 v[202:205], v147 offset:55328
	s_waitcnt lgkmcnt(1)
	v_mfma_f32_32x32x16_bf16 v[48:63], v[136:139], v[196:199], v[48:63]
	v_mfma_f32_32x32x16_bf16 v[32:47], v[136:139], v[132:135], v[32:47]
	v_mfma_f32_32x32x16_bf16 v[16:31], v[128:131], v[196:199], v[16:31]
	v_mfma_f32_32x32x16_bf16 v[0:15], v[128:131], v[132:135], v[0:15]
	ds_read_b128 v[128:131], v166 offset:23072
	ds_read_b128 v[132:135], v147 offset:59936
	s_waitcnt vmcnt(15)
	ds_write_b128 v146, v[96:99]
	s_waitcnt vmcnt(14)
	ds_write_b128 v146, v[100:103] offset:4608
	s_waitcnt vmcnt(13)
	ds_write_b128 v146, v[104:107] offset:9216
	s_waitcnt vmcnt(12)
	ds_write_b128 v146, v[108:111] offset:13824
	ds_read_b128 v[96:99], v166 offset:18496
	ds_read_b128 v[100:103], v166 offset:23104
	ds_read_b128 v[104:107], v147 offset:55360
	ds_read_b128 v[108:111], v147 offset:59968
	s_waitcnt vmcnt(11)
	ds_write_b128 v146, v[80:83] offset:36864
	s_waitcnt vmcnt(10)
	ds_write_b128 v146, v[84:87] offset:41472
	s_waitcnt vmcnt(9)
	ds_write_b128 v146, v[88:91] offset:46080
	s_waitcnt vmcnt(8)
	ds_write_b128 v146, v[92:95] offset:50688
	ds_read_b128 v[80:83], v166 offset:18528
	ds_read_b128 v[84:87], v166 offset:23136
	ds_read_b128 v[88:91], v147 offset:55392
	ds_read_b128 v[92:95], v147 offset:60000
	s_waitcnt lgkmcnt(0)
	s_barrier
	v_mfma_f32_32x32x16_bf16 v[48:63], v[140:143], v[202:205], v[48:63]
	v_mfma_f32_32x32x16_bf16 v[32:47], v[140:143], v[132:135], v[32:47]
	v_mfma_f32_32x32x16_bf16 v[16:31], v[128:131], v[202:205], v[16:31]
	v_mfma_f32_32x32x16_bf16 v[0:15], v[128:131], v[132:135], v[0:15]
	v_mfma_f32_32x32x16_bf16 v[48:63], v[96:99], v[104:107], v[48:63]
	v_mfma_f32_32x32x16_bf16 v[32:47], v[96:99], v[108:111], v[32:47]
	v_mfma_f32_32x32x16_bf16 v[16:31], v[100:103], v[104:107], v[16:31]
	v_mfma_f32_32x32x16_bf16 v[0:15], v[100:103], v[108:111], v[0:15]
	v_mfma_f32_32x32x16_bf16 v[48:63], v[80:83], v[88:91], v[48:63]
	v_mfma_f32_32x32x16_bf16 v[32:47], v[80:83], v[92:95], v[32:47]
	v_mfma_f32_32x32x16_bf16 v[16:31], v[84:87], v[88:91], v[16:31]
	v_mfma_f32_32x32x16_bf16 v[0:15], v[84:87], v[92:95], v[0:15]
	global_load_dwordx4 v[96:99], v160, s[10:11] offset:768
	global_load_dwordx4 v[100:103], v148, s[10:11] offset:768
	global_load_dwordx4 v[104:107], v150, s[10:11] offset:768
	global_load_dwordx4 v[108:111], v152, s[10:11] offset:768
	global_load_dwordx4 v[80:83], v[154:155], off offset:768
	global_load_dwordx4 v[84:87], v[156:157], off offset:768
	global_load_dwordx4 v[88:91], v[158:159], off offset:768
	global_load_dwordx4 v[92:95], v[164:165], off offset:768
	ds_read_b128 v[128:131], v166 offset:4608
	ds_read_b128 v[132:135], v147 offset:41472
	ds_read_b128 v[136:139], v166
	ds_read_b128 v[140:143], v166 offset:32
	ds_read_b128 v[196:199], v147 offset:36864
	ds_read_b128 v[202:205], v147 offset:36896
	s_waitcnt lgkmcnt(1)
	v_mfma_f32_32x32x16_bf16 v[48:63], v[136:139], v[196:199], v[48:63]
	v_mfma_f32_32x32x16_bf16 v[32:47], v[136:139], v[132:135], v[32:47]
	v_mfma_f32_32x32x16_bf16 v[16:31], v[128:131], v[196:199], v[16:31]
	v_mfma_f32_32x32x16_bf16 v[0:15], v[128:131], v[132:135], v[0:15]
	ds_read_b128 v[128:131], v166 offset:4640
	ds_read_b128 v[132:135], v147 offset:41504
	s_waitcnt vmcnt(15)
	ds_write_b128 v146, v[112:115] offset:18432
	s_waitcnt vmcnt(14)
	ds_write_b128 v146, v[116:119] offset:23040
	s_waitcnt vmcnt(13)
	ds_write_b128 v146, v[120:123] offset:27648
	s_waitcnt vmcnt(12)
	ds_write_b128 v146, v[124:127] offset:32256
	ds_read_b128 v[112:115], v166 offset:64
	ds_read_b128 v[116:119], v166 offset:4672
	ds_read_b128 v[120:123], v147 offset:36928
	ds_read_b128 v[124:127], v147 offset:41536
	s_waitcnt vmcnt(11)
	ds_write_b128 v146, v[64:67] offset:55296
	s_waitcnt vmcnt(10)
	ds_write_b128 v146, v[68:71] offset:59904
	s_waitcnt vmcnt(9)
	ds_write_b128 v146, v[72:75] offset:64512
	s_waitcnt vmcnt(8)
	ds_write_b128 v149, v[76:79] offset:13824
	ds_read_b128 v[64:67], v166 offset:96
	ds_read_b128 v[68:71], v166 offset:4704
	ds_read_b128 v[72:75], v147 offset:36960
	ds_read_b128 v[76:79], v147 offset:41568
	s_waitcnt lgkmcnt(0)
	s_barrier
	v_mfma_f32_32x32x16_bf16 v[48:63], v[140:143], v[202:205], v[48:63]
	v_mfma_f32_32x32x16_bf16 v[32:47], v[140:143], v[132:135], v[32:47]
	v_mfma_f32_32x32x16_bf16 v[16:31], v[128:131], v[202:205], v[16:31]
	v_mfma_f32_32x32x16_bf16 v[0:15], v[128:131], v[132:135], v[0:15]
	v_mfma_f32_32x32x16_bf16 v[48:63], v[112:115], v[120:123], v[48:63]
	v_mfma_f32_32x32x16_bf16 v[32:47], v[112:115], v[124:127], v[32:47]
	v_mfma_f32_32x32x16_bf16 v[16:31], v[116:119], v[120:123], v[16:31]
	v_mfma_f32_32x32x16_bf16 v[0:15], v[116:119], v[124:127], v[0:15]
	v_mfma_f32_32x32x16_bf16 v[48:63], v[64:67], v[72:75], v[48:63]
	v_mfma_f32_32x32x16_bf16 v[32:47], v[64:67], v[76:79], v[32:47]
	v_mfma_f32_32x32x16_bf16 v[16:31], v[68:71], v[72:75], v[16:31]
	v_mfma_f32_32x32x16_bf16 v[0:15], v[68:71], v[76:79], v[0:15]
	global_load_dwordx4 v[112:115], v160, s[10:11] offset:896
	global_load_dwordx4 v[116:119], v148, s[10:11] offset:896
	global_load_dwordx4 v[120:123], v150, s[10:11] offset:896
	global_load_dwordx4 v[124:127], v152, s[10:11] offset:896
	global_load_dwordx4 v[64:67], v[154:155], off offset:896
	global_load_dwordx4 v[68:71], v[156:157], off offset:896
	global_load_dwordx4 v[72:75], v[158:159], off offset:896
	global_load_dwordx4 v[76:79], v[164:165], off offset:896
	ds_read_b128 v[128:131], v166 offset:23040
	ds_read_b128 v[132:135], v147 offset:59904
	ds_read_b128 v[136:139], v166 offset:18432
	ds_read_b128 v[140:143], v166 offset:18464
	ds_read_b128 v[196:199], v147 offset:55296
	ds_read_b128 v[202:205], v147 offset:55328
	s_waitcnt lgkmcnt(1)
	v_mfma_f32_32x32x16_bf16 v[48:63], v[136:139], v[196:199], v[48:63]
	v_mfma_f32_32x32x16_bf16 v[32:47], v[136:139], v[132:135], v[32:47]
	v_mfma_f32_32x32x16_bf16 v[16:31], v[128:131], v[196:199], v[16:31]
	v_mfma_f32_32x32x16_bf16 v[0:15], v[128:131], v[132:135], v[0:15]
	ds_read_b128 v[128:131], v166 offset:23072
	ds_read_b128 v[132:135], v147 offset:59936
	s_waitcnt vmcnt(15)
	ds_write_b128 v146, v[96:99]
	s_waitcnt vmcnt(14)
	ds_write_b128 v146, v[100:103] offset:4608
	s_waitcnt vmcnt(13)
	ds_write_b128 v146, v[104:107] offset:9216
	s_waitcnt vmcnt(12)
	ds_write_b128 v146, v[108:111] offset:13824
	ds_read_b128 v[96:99], v166 offset:18496
	ds_read_b128 v[100:103], v166 offset:23104
	ds_read_b128 v[104:107], v147 offset:55360
	ds_read_b128 v[108:111], v147 offset:59968
	s_waitcnt vmcnt(11)
	ds_write_b128 v146, v[80:83] offset:36864
	s_waitcnt vmcnt(10)
	ds_write_b128 v146, v[84:87] offset:41472
	s_waitcnt vmcnt(9)
	ds_write_b128 v146, v[88:91] offset:46080
	s_waitcnt vmcnt(8)
	ds_write_b128 v146, v[92:95] offset:50688
	ds_read_b128 v[80:83], v166 offset:18528
	ds_read_b128 v[84:87], v166 offset:23136
	ds_read_b128 v[88:91], v147 offset:55392
	ds_read_b128 v[92:95], v147 offset:60000
	s_waitcnt lgkmcnt(0)
	s_barrier
	v_mfma_f32_32x32x16_bf16 v[48:63], v[140:143], v[202:205], v[48:63]
	v_mfma_f32_32x32x16_bf16 v[32:47], v[140:143], v[132:135], v[32:47]
	v_mfma_f32_32x32x16_bf16 v[16:31], v[128:131], v[202:205], v[16:31]
	v_mfma_f32_32x32x16_bf16 v[0:15], v[128:131], v[132:135], v[0:15]
	v_mfma_f32_32x32x16_bf16 v[48:63], v[96:99], v[104:107], v[48:63]
	v_mfma_f32_32x32x16_bf16 v[32:47], v[96:99], v[108:111], v[32:47]
	v_mfma_f32_32x32x16_bf16 v[16:31], v[100:103], v[104:107], v[16:31]
	v_mfma_f32_32x32x16_bf16 v[0:15], v[100:103], v[108:111], v[0:15]
	v_mfma_f32_32x32x16_bf16 v[48:63], v[80:83], v[88:91], v[48:63]
	v_mfma_f32_32x32x16_bf16 v[32:47], v[80:83], v[92:95], v[32:47]
	v_mfma_f32_32x32x16_bf16 v[16:31], v[84:87], v[88:91], v[16:31]
	v_mfma_f32_32x32x16_bf16 v[0:15], v[84:87], v[92:95], v[0:15]
	global_load_dwordx4 v[96:99], v160, s[10:11] offset:1024
	global_load_dwordx4 v[100:103], v148, s[10:11] offset:1024
	global_load_dwordx4 v[104:107], v150, s[10:11] offset:1024
	global_load_dwordx4 v[108:111], v152, s[10:11] offset:1024
	global_load_dwordx4 v[80:83], v[154:155], off offset:1024
	global_load_dwordx4 v[84:87], v[156:157], off offset:1024
	global_load_dwordx4 v[88:91], v[158:159], off offset:1024
	global_load_dwordx4 v[92:95], v[164:165], off offset:1024
	ds_read_b128 v[128:131], v166 offset:4608
	ds_read_b128 v[132:135], v147 offset:41472
	ds_read_b128 v[136:139], v166
	ds_read_b128 v[140:143], v166 offset:32
	ds_read_b128 v[196:199], v147 offset:36864
	ds_read_b128 v[202:205], v147 offset:36896
	s_waitcnt lgkmcnt(1)
	v_mfma_f32_32x32x16_bf16 v[48:63], v[136:139], v[196:199], v[48:63]
	v_mfma_f32_32x32x16_bf16 v[32:47], v[136:139], v[132:135], v[32:47]
	v_mfma_f32_32x32x16_bf16 v[16:31], v[128:131], v[196:199], v[16:31]
	v_mfma_f32_32x32x16_bf16 v[0:15], v[128:131], v[132:135], v[0:15]
	ds_read_b128 v[128:131], v166 offset:4640
	ds_read_b128 v[132:135], v147 offset:41504
	s_waitcnt vmcnt(15)
	ds_write_b128 v146, v[112:115] offset:18432
	s_waitcnt vmcnt(14)
	ds_write_b128 v146, v[116:119] offset:23040
	s_waitcnt vmcnt(13)
	ds_write_b128 v146, v[120:123] offset:27648
	s_waitcnt vmcnt(12)
	ds_write_b128 v146, v[124:127] offset:32256
	ds_read_b128 v[112:115], v166 offset:64
	ds_read_b128 v[116:119], v166 offset:4672
	ds_read_b128 v[120:123], v147 offset:36928
	ds_read_b128 v[124:127], v147 offset:41536
	s_waitcnt vmcnt(11)
	ds_write_b128 v146, v[64:67] offset:55296
	s_waitcnt vmcnt(10)
	ds_write_b128 v146, v[68:71] offset:59904
	s_waitcnt vmcnt(9)
	ds_write_b128 v146, v[72:75] offset:64512
	s_waitcnt vmcnt(8)
	ds_write_b128 v149, v[76:79] offset:13824
	ds_read_b128 v[64:67], v166 offset:96
	ds_read_b128 v[68:71], v166 offset:4704
	ds_read_b128 v[72:75], v147 offset:36960
	ds_read_b128 v[76:79], v147 offset:41568
	s_waitcnt lgkmcnt(0)
	s_barrier
	v_mfma_f32_32x32x16_bf16 v[48:63], v[140:143], v[202:205], v[48:63]
	v_mfma_f32_32x32x16_bf16 v[32:47], v[140:143], v[132:135], v[32:47]
	v_mfma_f32_32x32x16_bf16 v[16:31], v[128:131], v[202:205], v[16:31]
	v_mfma_f32_32x32x16_bf16 v[0:15], v[128:131], v[132:135], v[0:15]
	v_mfma_f32_32x32x16_bf16 v[48:63], v[112:115], v[120:123], v[48:63]
	v_mfma_f32_32x32x16_bf16 v[32:47], v[112:115], v[124:127], v[32:47]
	v_mfma_f32_32x32x16_bf16 v[16:31], v[116:119], v[120:123], v[16:31]
	v_mfma_f32_32x32x16_bf16 v[0:15], v[116:119], v[124:127], v[0:15]
	v_mfma_f32_32x32x16_bf16 v[48:63], v[64:67], v[72:75], v[48:63]
	v_mfma_f32_32x32x16_bf16 v[32:47], v[64:67], v[76:79], v[32:47]
	v_mfma_f32_32x32x16_bf16 v[16:31], v[68:71], v[72:75], v[16:31]
	v_mfma_f32_32x32x16_bf16 v[0:15], v[68:71], v[76:79], v[0:15]
	global_load_dwordx4 v[112:115], v160, s[10:11] offset:1152
	global_load_dwordx4 v[116:119], v148, s[10:11] offset:1152
	global_load_dwordx4 v[120:123], v150, s[10:11] offset:1152
	global_load_dwordx4 v[124:127], v152, s[10:11] offset:1152
	global_load_dwordx4 v[64:67], v[154:155], off offset:1152
	global_load_dwordx4 v[68:71], v[156:157], off offset:1152
	global_load_dwordx4 v[72:75], v[158:159], off offset:1152
	global_load_dwordx4 v[76:79], v[164:165], off offset:1152
	ds_read_b128 v[128:131], v166 offset:23040
	ds_read_b128 v[132:135], v147 offset:59904
	ds_read_b128 v[136:139], v166 offset:18432
	ds_read_b128 v[140:143], v166 offset:18464
	ds_read_b128 v[196:199], v147 offset:55296
	ds_read_b128 v[202:205], v147 offset:55328
	s_waitcnt lgkmcnt(1)
	v_mfma_f32_32x32x16_bf16 v[48:63], v[136:139], v[196:199], v[48:63]
	v_mfma_f32_32x32x16_bf16 v[32:47], v[136:139], v[132:135], v[32:47]
	v_mfma_f32_32x32x16_bf16 v[16:31], v[128:131], v[196:199], v[16:31]
	v_mfma_f32_32x32x16_bf16 v[0:15], v[128:131], v[132:135], v[0:15]
	ds_read_b128 v[128:131], v166 offset:23072
	ds_read_b128 v[132:135], v147 offset:59936
	s_waitcnt vmcnt(15)
	ds_write_b128 v146, v[96:99]
	s_waitcnt vmcnt(14)
	ds_write_b128 v146, v[100:103] offset:4608
	s_waitcnt vmcnt(13)
	ds_write_b128 v146, v[104:107] offset:9216
	s_waitcnt vmcnt(12)
	ds_write_b128 v146, v[108:111] offset:13824
	ds_read_b128 v[96:99], v166 offset:18496
	ds_read_b128 v[100:103], v166 offset:23104
	ds_read_b128 v[104:107], v147 offset:55360
	ds_read_b128 v[108:111], v147 offset:59968
	s_waitcnt vmcnt(11)
	ds_write_b128 v146, v[80:83] offset:36864
	s_waitcnt vmcnt(10)
	ds_write_b128 v146, v[84:87] offset:41472
	s_waitcnt vmcnt(9)
	ds_write_b128 v146, v[88:91] offset:46080
	s_waitcnt vmcnt(8)
	ds_write_b128 v146, v[92:95] offset:50688
	ds_read_b128 v[80:83], v166 offset:18528
	ds_read_b128 v[84:87], v166 offset:23136
	ds_read_b128 v[88:91], v147 offset:55392
	ds_read_b128 v[92:95], v147 offset:60000
	s_waitcnt lgkmcnt(0)
	s_barrier
	v_mfma_f32_32x32x16_bf16 v[48:63], v[140:143], v[202:205], v[48:63]
	v_mfma_f32_32x32x16_bf16 v[32:47], v[140:143], v[132:135], v[32:47]
	v_mfma_f32_32x32x16_bf16 v[16:31], v[128:131], v[202:205], v[16:31]
	v_mfma_f32_32x32x16_bf16 v[0:15], v[128:131], v[132:135], v[0:15]
	v_mfma_f32_32x32x16_bf16 v[48:63], v[96:99], v[104:107], v[48:63]
	v_mfma_f32_32x32x16_bf16 v[32:47], v[96:99], v[108:111], v[32:47]
	v_mfma_f32_32x32x16_bf16 v[16:31], v[100:103], v[104:107], v[16:31]
	v_mfma_f32_32x32x16_bf16 v[0:15], v[100:103], v[108:111], v[0:15]
	v_mfma_f32_32x32x16_bf16 v[48:63], v[80:83], v[88:91], v[48:63]
	v_mfma_f32_32x32x16_bf16 v[32:47], v[80:83], v[92:95], v[32:47]
	v_mfma_f32_32x32x16_bf16 v[16:31], v[84:87], v[88:91], v[16:31]
	v_mfma_f32_32x32x16_bf16 v[0:15], v[84:87], v[92:95], v[0:15]
	global_load_dwordx4 v[96:99], v160, s[10:11] offset:1280
	global_load_dwordx4 v[100:103], v148, s[10:11] offset:1280
	global_load_dwordx4 v[104:107], v150, s[10:11] offset:1280
	global_load_dwordx4 v[108:111], v152, s[10:11] offset:1280
	global_load_dwordx4 v[80:83], v[154:155], off offset:1280
	global_load_dwordx4 v[84:87], v[156:157], off offset:1280
	global_load_dwordx4 v[88:91], v[158:159], off offset:1280
	global_load_dwordx4 v[92:95], v[164:165], off offset:1280
	ds_read_b128 v[128:131], v166 offset:4608
	ds_read_b128 v[132:135], v147 offset:41472
	ds_read_b128 v[136:139], v166
	ds_read_b128 v[140:143], v166 offset:32
	ds_read_b128 v[196:199], v147 offset:36864
	ds_read_b128 v[202:205], v147 offset:36896
	s_waitcnt lgkmcnt(1)
	v_mfma_f32_32x32x16_bf16 v[48:63], v[136:139], v[196:199], v[48:63]
	v_mfma_f32_32x32x16_bf16 v[32:47], v[136:139], v[132:135], v[32:47]
	v_mfma_f32_32x32x16_bf16 v[16:31], v[128:131], v[196:199], v[16:31]
	v_mfma_f32_32x32x16_bf16 v[0:15], v[128:131], v[132:135], v[0:15]
	ds_read_b128 v[128:131], v166 offset:4640
	ds_read_b128 v[132:135], v147 offset:41504
	s_waitcnt vmcnt(15)
	ds_write_b128 v146, v[112:115] offset:18432
	s_waitcnt vmcnt(14)
	ds_write_b128 v146, v[116:119] offset:23040
	s_waitcnt vmcnt(13)
	ds_write_b128 v146, v[120:123] offset:27648
	s_waitcnt vmcnt(12)
	ds_write_b128 v146, v[124:127] offset:32256
	ds_read_b128 v[112:115], v166 offset:64
	ds_read_b128 v[116:119], v166 offset:4672
	ds_read_b128 v[120:123], v147 offset:36928
	ds_read_b128 v[124:127], v147 offset:41536
	s_waitcnt vmcnt(11)
	ds_write_b128 v146, v[64:67] offset:55296
	s_waitcnt vmcnt(10)
	ds_write_b128 v146, v[68:71] offset:59904
	s_waitcnt vmcnt(9)
	ds_write_b128 v146, v[72:75] offset:64512
	s_waitcnt vmcnt(8)
	ds_write_b128 v149, v[76:79] offset:13824
	ds_read_b128 v[64:67], v166 offset:96
	ds_read_b128 v[68:71], v166 offset:4704
	ds_read_b128 v[72:75], v147 offset:36960
	ds_read_b128 v[76:79], v147 offset:41568
	s_waitcnt lgkmcnt(0)
	s_barrier
	v_mfma_f32_32x32x16_bf16 v[48:63], v[140:143], v[202:205], v[48:63]
	v_mfma_f32_32x32x16_bf16 v[32:47], v[140:143], v[132:135], v[32:47]
	v_mfma_f32_32x32x16_bf16 v[16:31], v[128:131], v[202:205], v[16:31]
	v_mfma_f32_32x32x16_bf16 v[0:15], v[128:131], v[132:135], v[0:15]
	v_mfma_f32_32x32x16_bf16 v[48:63], v[112:115], v[120:123], v[48:63]
	v_mfma_f32_32x32x16_bf16 v[32:47], v[112:115], v[124:127], v[32:47]
	v_mfma_f32_32x32x16_bf16 v[16:31], v[116:119], v[120:123], v[16:31]
	v_mfma_f32_32x32x16_bf16 v[0:15], v[116:119], v[124:127], v[0:15]
	v_mfma_f32_32x32x16_bf16 v[48:63], v[64:67], v[72:75], v[48:63]
	v_mfma_f32_32x32x16_bf16 v[32:47], v[64:67], v[76:79], v[32:47]
	v_mfma_f32_32x32x16_bf16 v[16:31], v[68:71], v[72:75], v[16:31]
	v_mfma_f32_32x32x16_bf16 v[0:15], v[68:71], v[76:79], v[0:15]
	global_load_dwordx4 v[112:115], v160, s[10:11] offset:1408
	global_load_dwordx4 v[116:119], v148, s[10:11] offset:1408
	global_load_dwordx4 v[120:123], v150, s[10:11] offset:1408
	global_load_dwordx4 v[124:127], v152, s[10:11] offset:1408
	global_load_dwordx4 v[64:67], v[154:155], off offset:1408
	global_load_dwordx4 v[68:71], v[156:157], off offset:1408
	global_load_dwordx4 v[72:75], v[158:159], off offset:1408
	global_load_dwordx4 v[76:79], v[164:165], off offset:1408
	ds_read_b128 v[128:131], v166 offset:23040
	ds_read_b128 v[132:135], v147 offset:59904
	ds_read_b128 v[136:139], v166 offset:18432
	ds_read_b128 v[140:143], v166 offset:18464
	ds_read_b128 v[196:199], v147 offset:55296
	ds_read_b128 v[202:205], v147 offset:55328
	s_waitcnt lgkmcnt(1)
	v_mfma_f32_32x32x16_bf16 v[48:63], v[136:139], v[196:199], v[48:63]
	v_mfma_f32_32x32x16_bf16 v[32:47], v[136:139], v[132:135], v[32:47]
	v_mfma_f32_32x32x16_bf16 v[16:31], v[128:131], v[196:199], v[16:31]
	v_mfma_f32_32x32x16_bf16 v[0:15], v[128:131], v[132:135], v[0:15]
	ds_read_b128 v[128:131], v166 offset:23072
	ds_read_b128 v[132:135], v147 offset:59936
	s_waitcnt vmcnt(15)
	ds_write_b128 v146, v[96:99]
	s_waitcnt vmcnt(14)
	ds_write_b128 v146, v[100:103] offset:4608
	s_waitcnt vmcnt(13)
	ds_write_b128 v146, v[104:107] offset:9216
	s_waitcnt vmcnt(12)
	ds_write_b128 v146, v[108:111] offset:13824
	ds_read_b128 v[96:99], v166 offset:18496
	ds_read_b128 v[100:103], v166 offset:23104
	ds_read_b128 v[104:107], v147 offset:55360
	ds_read_b128 v[108:111], v147 offset:59968
	s_waitcnt vmcnt(11)
	ds_write_b128 v146, v[80:83] offset:36864
	s_waitcnt vmcnt(10)
	ds_write_b128 v146, v[84:87] offset:41472
	s_waitcnt vmcnt(9)
	ds_write_b128 v146, v[88:91] offset:46080
	s_waitcnt vmcnt(8)
	ds_write_b128 v146, v[92:95] offset:50688
	ds_read_b128 v[80:83], v166 offset:18528
	ds_read_b128 v[84:87], v166 offset:23136
	ds_read_b128 v[88:91], v147 offset:55392
	ds_read_b128 v[92:95], v147 offset:60000
	s_waitcnt lgkmcnt(0)
	s_barrier
	v_mfma_f32_32x32x16_bf16 v[48:63], v[140:143], v[202:205], v[48:63]
	v_mfma_f32_32x32x16_bf16 v[32:47], v[140:143], v[132:135], v[32:47]
	v_mfma_f32_32x32x16_bf16 v[16:31], v[128:131], v[202:205], v[16:31]
	v_mfma_f32_32x32x16_bf16 v[0:15], v[128:131], v[132:135], v[0:15]
	v_mfma_f32_32x32x16_bf16 v[48:63], v[96:99], v[104:107], v[48:63]
	v_mfma_f32_32x32x16_bf16 v[32:47], v[96:99], v[108:111], v[32:47]
	v_mfma_f32_32x32x16_bf16 v[16:31], v[100:103], v[104:107], v[16:31]
	v_mfma_f32_32x32x16_bf16 v[0:15], v[100:103], v[108:111], v[0:15]
	v_mfma_f32_32x32x16_bf16 v[48:63], v[80:83], v[88:91], v[48:63]
	v_mfma_f32_32x32x16_bf16 v[32:47], v[80:83], v[92:95], v[32:47]
	v_mfma_f32_32x32x16_bf16 v[16:31], v[84:87], v[88:91], v[16:31]
	v_mfma_f32_32x32x16_bf16 v[0:15], v[84:87], v[92:95], v[0:15]
	global_load_dwordx4 v[80:83], v160, s[10:11] offset:1536
	global_load_dwordx4 v[84:87], v148, s[10:11] offset:1536
	global_load_dwordx4 v[88:91], v150, s[10:11] offset:1536
	global_load_dwordx4 v[92:95], v152, s[10:11] offset:1536
	global_load_dwordx4 v[96:99], v[154:155], off offset:1536
	global_load_dwordx4 v[100:103], v[156:157], off offset:1536
	global_load_dwordx4 v[104:107], v[158:159], off offset:1536
	global_load_dwordx4 v[108:111], v[164:165], off offset:1536
	ds_read_b128 v[128:131], v166 offset:4608
	ds_read_b128 v[132:135], v147 offset:41472
	ds_read_b128 v[136:139], v166
	ds_read_b128 v[140:143], v166 offset:32
	ds_read_b128 v[196:199], v147 offset:36864
	ds_read_b128 v[202:205], v147 offset:36896
	s_waitcnt lgkmcnt(1)
	v_mfma_f32_32x32x16_bf16 v[48:63], v[136:139], v[196:199], v[48:63]
	v_mfma_f32_32x32x16_bf16 v[32:47], v[136:139], v[132:135], v[32:47]
	v_mfma_f32_32x32x16_bf16 v[16:31], v[128:131], v[196:199], v[16:31]
	v_mfma_f32_32x32x16_bf16 v[0:15], v[128:131], v[132:135], v[0:15]
	ds_read_b128 v[128:131], v166 offset:4640
	ds_read_b128 v[132:135], v147 offset:41504
	s_waitcnt vmcnt(15)
	ds_write_b128 v146, v[112:115] offset:18432
	s_waitcnt vmcnt(14)
	ds_write_b128 v146, v[116:119] offset:23040
	s_waitcnt vmcnt(13)
	ds_write_b128 v146, v[120:123] offset:27648
	s_waitcnt vmcnt(12)
	ds_write_b128 v146, v[124:127] offset:32256
	ds_read_b128 v[112:115], v166 offset:64
	ds_read_b128 v[116:119], v166 offset:4672
	ds_read_b128 v[120:123], v147 offset:36928
	ds_read_b128 v[124:127], v147 offset:41536
	s_waitcnt vmcnt(11)
	ds_write_b128 v146, v[64:67] offset:55296
	s_waitcnt vmcnt(10)
	ds_write_b128 v146, v[68:71] offset:59904
	s_waitcnt vmcnt(9)
	ds_write_b128 v146, v[72:75] offset:64512
	s_waitcnt vmcnt(8)
	ds_write_b128 v149, v[76:79] offset:13824
	ds_read_b128 v[64:67], v166 offset:96
	ds_read_b128 v[68:71], v166 offset:4704
	ds_read_b128 v[72:75], v147 offset:36960
	ds_read_b128 v[76:79], v147 offset:41568
	s_waitcnt lgkmcnt(0)
	s_barrier
	v_mfma_f32_32x32x16_bf16 v[48:63], v[140:143], v[202:205], v[48:63]
	v_mfma_f32_32x32x16_bf16 v[32:47], v[140:143], v[132:135], v[32:47]
	v_mfma_f32_32x32x16_bf16 v[16:31], v[128:131], v[202:205], v[16:31]
	v_mfma_f32_32x32x16_bf16 v[0:15], v[128:131], v[132:135], v[0:15]
	v_mfma_f32_32x32x16_bf16 v[48:63], v[112:115], v[120:123], v[48:63]
	v_mfma_f32_32x32x16_bf16 v[32:47], v[112:115], v[124:127], v[32:47]
	v_mfma_f32_32x32x16_bf16 v[16:31], v[116:119], v[120:123], v[16:31]
	v_mfma_f32_32x32x16_bf16 v[0:15], v[116:119], v[124:127], v[0:15]
	v_mfma_f32_32x32x16_bf16 v[48:63], v[64:67], v[72:75], v[48:63]
	v_mfma_f32_32x32x16_bf16 v[32:47], v[64:67], v[76:79], v[32:47]
	v_mfma_f32_32x32x16_bf16 v[16:31], v[68:71], v[72:75], v[16:31]
	v_mfma_f32_32x32x16_bf16 v[0:15], v[68:71], v[76:79], v[0:15]
	global_load_dwordx4 v[64:67], v160, s[10:11] offset:1664
	global_load_dwordx4 v[68:71], v148, s[10:11] offset:1664
	global_load_dwordx4 v[72:75], v150, s[10:11] offset:1664
	global_load_dwordx4 v[76:79], v152, s[10:11] offset:1664
	global_load_dwordx4 v[112:115], v[154:155], off offset:1664
	global_load_dwordx4 v[116:119], v[156:157], off offset:1664
	global_load_dwordx4 v[120:123], v[158:159], off offset:1664
	global_load_dwordx4 v[124:127], v[164:165], off offset:1664
	ds_read_b128 v[128:131], v166 offset:23040
	ds_read_b128 v[132:135], v147 offset:59904
	ds_read_b128 v[136:139], v166 offset:18432
	ds_read_b128 v[140:143], v166 offset:18464
	ds_read_b128 v[196:199], v147 offset:55296
	ds_read_b128 v[202:205], v147 offset:55328
	s_waitcnt lgkmcnt(1)
	v_mfma_f32_32x32x16_bf16 v[48:63], v[136:139], v[196:199], v[48:63]
	v_mfma_f32_32x32x16_bf16 v[32:47], v[136:139], v[132:135], v[32:47]
	v_mfma_f32_32x32x16_bf16 v[16:31], v[128:131], v[196:199], v[16:31]
	v_mfma_f32_32x32x16_bf16 v[0:15], v[128:131], v[132:135], v[0:15]
	ds_read_b128 v[128:131], v166 offset:23072
	ds_read_b128 v[132:135], v147 offset:59936
	s_waitcnt vmcnt(15)
	ds_write_b128 v146, v[80:83]
	s_waitcnt vmcnt(14)
	ds_write_b128 v146, v[84:87] offset:4608
	s_waitcnt vmcnt(13)
	ds_write_b128 v146, v[88:91] offset:9216
	s_waitcnt vmcnt(12)
	ds_write_b128 v146, v[92:95] offset:13824
	ds_read_b128 v[80:83], v166 offset:18496
	ds_read_b128 v[84:87], v166 offset:23104
	ds_read_b128 v[88:91], v147 offset:55360
	ds_read_b128 v[92:95], v147 offset:59968
	s_waitcnt vmcnt(11)
	ds_write_b128 v146, v[96:99] offset:36864
	s_waitcnt vmcnt(10)
	ds_write_b128 v146, v[100:103] offset:41472
	s_waitcnt vmcnt(9)
	ds_write_b128 v146, v[104:107] offset:46080
	s_waitcnt vmcnt(8)
	ds_write_b128 v146, v[108:111] offset:50688
	s_waitcnt lgkmcnt(14)
	v_mfma_f32_32x32x16_bf16 v[48:63], v[140:143], v[202:205], v[48:63]
	s_waitcnt lgkmcnt(12)
	v_mfma_f32_32x32x16_bf16 v[32:47], v[140:143], v[132:135], v[32:47]
	v_mfma_f32_32x32x16_bf16 v[16:31], v[128:131], v[202:205], v[16:31]
	v_mfma_f32_32x32x16_bf16 v[0:15], v[128:131], v[132:135], v[0:15]
	s_waitcnt lgkmcnt(5)
	v_mfma_f32_32x32x16_bf16 v[48:63], v[80:83], v[88:91], v[48:63]
	s_waitcnt lgkmcnt(4)
	v_mfma_f32_32x32x16_bf16 v[32:47], v[80:83], v[92:95], v[32:47]
	v_mfma_f32_32x32x16_bf16 v[16:31], v[84:87], v[88:91], v[16:31]
	v_mfma_f32_32x32x16_bf16 v[0:15], v[84:87], v[92:95], v[0:15]
	ds_read_b128 v[80:83], v166 offset:18528
	ds_read_b128 v[84:87], v166 offset:23136
	ds_read_b128 v[88:91], v147 offset:55392
	ds_read_b128 v[92:95], v147 offset:60000
	s_waitcnt lgkmcnt(0)
	s_barrier
	v_mfma_f32_32x32x16_bf16 v[48:63], v[80:83], v[88:91], v[48:63]
	v_mfma_f32_32x32x16_bf16 v[32:47], v[80:83], v[92:95], v[32:47]
	v_mfma_f32_32x32x16_bf16 v[16:31], v[84:87], v[88:91], v[16:31]
	v_mfma_f32_32x32x16_bf16 v[0:15], v[84:87], v[92:95], v[0:15]
	global_load_dwordx4 v[80:83], v160, s[10:11] offset:1792
	global_load_dwordx4 v[84:87], v148, s[10:11] offset:1792
	global_load_dwordx4 v[88:91], v150, s[10:11] offset:1792
	global_load_dwordx4 v[92:95], v152, s[10:11] offset:1792
	global_load_dwordx4 v[96:99], v[154:155], off offset:1792
	global_load_dwordx4 v[100:103], v[156:157], off offset:1792
	global_load_dwordx4 v[104:107], v[158:159], off offset:1792
	global_load_dwordx4 v[108:111], v[164:165], off offset:1792
	ds_read_b128 v[128:131], v166 offset:4608
	ds_read_b128 v[132:135], v147 offset:41472
	ds_read_b128 v[136:139], v166
	ds_read_b128 v[140:143], v166 offset:32
	ds_read_b128 v[196:199], v147 offset:36864
	ds_read_b128 v[202:205], v147 offset:36896
	s_waitcnt lgkmcnt(1)
	v_mfma_f32_32x32x16_bf16 v[48:63], v[136:139], v[196:199], v[48:63]
	v_mfma_f32_32x32x16_bf16 v[32:47], v[136:139], v[132:135], v[32:47]
	v_mfma_f32_32x32x16_bf16 v[16:31], v[128:131], v[196:199], v[16:31]
	v_mfma_f32_32x32x16_bf16 v[0:15], v[128:131], v[132:135], v[0:15]
	ds_read_b128 v[128:131], v166 offset:4640
	ds_read_b128 v[132:135], v147 offset:41504
	s_waitcnt vmcnt(15)
	ds_write_b128 v146, v[64:67] offset:18432
	s_waitcnt vmcnt(14)
	ds_write_b128 v146, v[68:71] offset:23040
	s_waitcnt vmcnt(13)
	ds_write_b128 v146, v[72:75] offset:27648
	s_waitcnt vmcnt(12)
	ds_write_b128 v146, v[76:79] offset:32256
	ds_read_b128 v[64:67], v166 offset:64
	ds_read_b128 v[68:71], v166 offset:4672
	ds_read_b128 v[72:75], v147 offset:36928
	ds_read_b128 v[76:79], v147 offset:41536
	s_waitcnt vmcnt(11)
	ds_write_b128 v146, v[112:115] offset:55296
	s_waitcnt vmcnt(10)
	ds_write_b128 v146, v[116:119] offset:59904
	s_waitcnt vmcnt(9)
	ds_write_b128 v146, v[120:123] offset:64512
	s_waitcnt vmcnt(8)
	ds_write_b128 v149, v[124:127] offset:13824
	s_waitcnt lgkmcnt(14)
	v_mfma_f32_32x32x16_bf16 v[48:63], v[140:143], v[202:205], v[48:63]
	s_waitcnt lgkmcnt(12)
	v_mfma_f32_32x32x16_bf16 v[32:47], v[140:143], v[132:135], v[32:47]
	v_mfma_f32_32x32x16_bf16 v[16:31], v[128:131], v[202:205], v[16:31]
	v_mfma_f32_32x32x16_bf16 v[0:15], v[128:131], v[132:135], v[0:15]
	s_waitcnt lgkmcnt(5)
	v_mfma_f32_32x32x16_bf16 v[48:63], v[64:67], v[72:75], v[48:63]
	s_waitcnt lgkmcnt(4)
	v_mfma_f32_32x32x16_bf16 v[32:47], v[64:67], v[76:79], v[32:47]
	v_mfma_f32_32x32x16_bf16 v[16:31], v[68:71], v[72:75], v[16:31]
	v_mfma_f32_32x32x16_bf16 v[0:15], v[68:71], v[76:79], v[0:15]
	ds_read_b128 v[64:67], v166 offset:96
	ds_read_b128 v[68:71], v166 offset:4704
	ds_read_b128 v[72:75], v147 offset:36960
	ds_read_b128 v[76:79], v147 offset:41568
	s_waitcnt lgkmcnt(0)
	s_barrier
	v_mfma_f32_32x32x16_bf16 v[48:63], v[64:67], v[72:75], v[48:63]
	v_mfma_f32_32x32x16_bf16 v[32:47], v[64:67], v[76:79], v[32:47]
	v_mfma_f32_32x32x16_bf16 v[16:31], v[68:71], v[72:75], v[16:31]
	v_mfma_f32_32x32x16_bf16 v[0:15], v[68:71], v[76:79], v[0:15]
	global_load_dwordx4 v[64:67], v160, s[10:11] offset:1920
	global_load_dwordx4 v[68:71], v148, s[10:11] offset:1920
	global_load_dwordx4 v[72:75], v150, s[10:11] offset:1920
	global_load_dwordx4 v[76:79], v152, s[10:11] offset:1920
	global_load_dwordx4 v[112:115], v[154:155], off offset:1920
	global_load_dwordx4 v[116:119], v[156:157], off offset:1920
	global_load_dwordx4 v[120:123], v[158:159], off offset:1920
	global_load_dwordx4 v[124:127], v[164:165], off offset:1920
	ds_read_b128 v[128:131], v166 offset:23040
	ds_read_b128 v[132:135], v147 offset:59904
	ds_read_b128 v[136:139], v166 offset:18432
	ds_read_b128 v[140:143], v166 offset:18464
	ds_read_b128 v[150:153], v147 offset:55296
	ds_read_b128 v[154:157], v147 offset:55328
	s_waitcnt lgkmcnt(1)
	v_mfma_f32_32x32x16_bf16 v[48:63], v[136:139], v[150:153], v[48:63]
	v_mfma_f32_32x32x16_bf16 v[32:47], v[136:139], v[132:135], v[32:47]
	v_mfma_f32_32x32x16_bf16 v[16:31], v[128:131], v[150:153], v[16:31]
	v_mfma_f32_32x32x16_bf16 v[0:15], v[128:131], v[132:135], v[0:15]
	ds_read_b128 v[128:131], v166 offset:23072
	ds_read_b128 v[132:135], v147 offset:59936
	s_waitcnt vmcnt(15)
	ds_write_b128 v146, v[80:83]
	s_waitcnt vmcnt(14)
	ds_write_b128 v146, v[84:87] offset:4608
	s_waitcnt vmcnt(13)
	ds_write_b128 v146, v[88:91] offset:9216
	s_waitcnt vmcnt(12)
	ds_write_b128 v146, v[92:95] offset:13824
	ds_read_b128 v[80:83], v166 offset:18496
	ds_read_b128 v[84:87], v166 offset:23104
	ds_read_b128 v[88:91], v147 offset:55360
	ds_read_b128 v[92:95], v147 offset:59968
	s_waitcnt vmcnt(11)
	ds_write_b128 v146, v[96:99] offset:36864
	s_waitcnt vmcnt(10)
	ds_write_b128 v146, v[100:103] offset:41472
	s_waitcnt vmcnt(9)
	ds_write_b128 v146, v[104:107] offset:46080
	s_waitcnt vmcnt(8)
	ds_write_b128 v146, v[108:111] offset:50688
	s_waitcnt lgkmcnt(14)
	v_mfma_f32_32x32x16_bf16 v[48:63], v[140:143], v[154:157], v[48:63]
	s_waitcnt lgkmcnt(12)
	v_mfma_f32_32x32x16_bf16 v[32:47], v[140:143], v[132:135], v[32:47]
	v_mfma_f32_32x32x16_bf16 v[16:31], v[128:131], v[154:157], v[16:31]
	v_mfma_f32_32x32x16_bf16 v[0:15], v[128:131], v[132:135], v[0:15]
	s_waitcnt lgkmcnt(5)
	v_mfma_f32_32x32x16_bf16 v[48:63], v[80:83], v[88:91], v[48:63]
	s_waitcnt lgkmcnt(4)
	v_mfma_f32_32x32x16_bf16 v[32:47], v[80:83], v[92:95], v[32:47]
	v_mfma_f32_32x32x16_bf16 v[16:31], v[84:87], v[88:91], v[16:31]
	v_mfma_f32_32x32x16_bf16 v[0:15], v[84:87], v[92:95], v[0:15]
	ds_read_b128 v[80:83], v166 offset:18528
	ds_read_b128 v[84:87], v166 offset:23136
	ds_read_b128 v[88:91], v147 offset:55392
	ds_read_b128 v[92:95], v147 offset:60000
	s_waitcnt lgkmcnt(0)
	s_barrier
	v_mfma_f32_32x32x16_bf16 v[48:63], v[80:83], v[88:91], v[48:63]
	v_mfma_f32_32x32x16_bf16 v[32:47], v[80:83], v[92:95], v[32:47]
	v_mfma_f32_32x32x16_bf16 v[16:31], v[84:87], v[88:91], v[16:31]
	v_mfma_f32_32x32x16_bf16 v[0:15], v[84:87], v[92:95], v[0:15]
	ds_read_b128 v[80:83], v166 offset:4608
	ds_read_b128 v[84:87], v147 offset:41472
	ds_read_b128 v[88:91], v166
	ds_read_b128 v[92:95], v166 offset:32
	ds_read_b128 v[96:99], v147 offset:36864
	ds_read_b128 v[100:103], v147 offset:36896
	s_waitcnt lgkmcnt(1)
	v_mfma_f32_32x32x16_bf16 v[48:63], v[88:91], v[96:99], v[48:63]
	v_mfma_f32_32x32x16_bf16 v[32:47], v[88:91], v[84:87], v[32:47]
	v_mfma_f32_32x32x16_bf16 v[16:31], v[80:83], v[96:99], v[16:31]
	v_mfma_f32_32x32x16_bf16 v[0:15], v[80:83], v[84:87], v[0:15]
	ds_read_b128 v[80:83], v166 offset:4640
	ds_read_b128 v[84:87], v147 offset:41504
	s_waitcnt vmcnt(7)
	ds_write_b128 v146, v[64:67] offset:18432
	s_waitcnt vmcnt(6)
	ds_write_b128 v146, v[68:71] offset:23040
	s_waitcnt vmcnt(5)
	ds_write_b128 v146, v[72:75] offset:27648
	s_waitcnt vmcnt(4)
	ds_write_b128 v146, v[76:79] offset:32256
	ds_read_b128 v[64:67], v166 offset:64
	ds_read_b128 v[68:71], v166 offset:4672
	ds_read_b128 v[72:75], v147 offset:36928
	ds_read_b128 v[76:79], v147 offset:41536
	s_waitcnt vmcnt(3)
	ds_write_b128 v146, v[112:115] offset:55296
	s_waitcnt vmcnt(2)
	ds_write_b128 v146, v[116:119] offset:59904
	s_waitcnt vmcnt(1)
	ds_write_b128 v146, v[120:123] offset:64512
	s_waitcnt vmcnt(0)
	ds_write_b128 v149, v[124:127] offset:13824
	s_waitcnt lgkmcnt(14)
	v_mfma_f32_32x32x16_bf16 v[48:63], v[92:95], v[100:103], v[48:63]
	s_waitcnt lgkmcnt(12)
	v_mfma_f32_32x32x16_bf16 v[32:47], v[92:95], v[84:87], v[32:47]
	v_mfma_f32_32x32x16_bf16 v[16:31], v[80:83], v[100:103], v[16:31]
	v_mfma_f32_32x32x16_bf16 v[0:15], v[80:83], v[84:87], v[0:15]
	s_waitcnt lgkmcnt(5)
	v_mfma_f32_32x32x16_bf16 v[48:63], v[64:67], v[72:75], v[48:63]
	s_waitcnt lgkmcnt(4)
	v_mfma_f32_32x32x16_bf16 v[32:47], v[64:67], v[76:79], v[32:47]
	v_mfma_f32_32x32x16_bf16 v[16:31], v[68:71], v[72:75], v[16:31]
	v_mfma_f32_32x32x16_bf16 v[0:15], v[68:71], v[76:79], v[0:15]
	ds_read_b128 v[64:67], v166 offset:96
	ds_read_b128 v[68:71], v166 offset:4704
	ds_read_b128 v[72:75], v147 offset:36960
	ds_read_b128 v[76:79], v147 offset:41568
	s_waitcnt lgkmcnt(0)
	s_barrier
	v_mfma_f32_32x32x16_bf16 v[48:63], v[64:67], v[72:75], v[48:63]
	v_mfma_f32_32x32x16_bf16 v[32:47], v[64:67], v[76:79], v[32:47]
	v_mfma_f32_32x32x16_bf16 v[16:31], v[68:71], v[72:75], v[16:31]
	v_mfma_f32_32x32x16_bf16 v[0:15], v[68:71], v[76:79], v[0:15]
	ds_read_b128 v[64:67], v166 offset:23040
	ds_read_b128 v[68:71], v147 offset:59904
	ds_read_b128 v[72:75], v166 offset:18432
	ds_read_b128 v[76:79], v166 offset:18464
	ds_read_b128 v[80:83], v147 offset:55296
	ds_read_b128 v[84:87], v147 offset:55328
	s_waitcnt lgkmcnt(1)
	v_mfma_f32_32x32x16_bf16 v[48:63], v[72:75], v[80:83], v[48:63]
	v_mfma_f32_32x32x16_bf16 v[32:47], v[72:75], v[68:71], v[32:47]
	v_mfma_f32_32x32x16_bf16 v[16:31], v[64:67], v[80:83], v[16:31]
	v_mfma_f32_32x32x16_bf16 v[0:15], v[64:67], v[68:71], v[0:15]
	ds_read_b128 v[64:67], v166 offset:23072
	ds_read_b128 v[68:71], v147 offset:59936
	s_waitcnt lgkmcnt(2)
	v_mfma_f32_32x32x16_bf16 v[48:63], v[76:79], v[84:87], v[48:63]
	s_waitcnt lgkmcnt(0)
	v_mfma_f32_32x32x16_bf16 v[32:47], v[76:79], v[68:71], v[32:47]
	v_mfma_f32_32x32x16_bf16 v[16:31], v[64:67], v[84:87], v[16:31]
	v_mfma_f32_32x32x16_bf16 v[0:15], v[64:67], v[68:71], v[0:15]
	ds_read_b128 v[64:67], v147 offset:59968
	ds_read_b128 v[68:71], v147 offset:55360
	ds_read_b128 v[72:75], v166 offset:23104
	ds_read_b128 v[76:79], v166 offset:18496
	s_waitcnt lgkmcnt(0)
	v_mfma_f32_32x32x16_bf16 v[48:63], v[76:79], v[68:71], v[48:63]
	v_mfma_f32_32x32x16_bf16 v[32:47], v[76:79], v[64:67], v[32:47]
	v_mfma_f32_32x32x16_bf16 v[16:31], v[72:75], v[68:71], v[16:31]
	v_mfma_f32_32x32x16_bf16 v[0:15], v[72:75], v[64:67], v[0:15]
	ds_read_b128 v[64:67], v147 offset:60000
	ds_read_b128 v[68:71], v147 offset:55392
	ds_read_b128 v[72:75], v166 offset:23136
	ds_read_b128 v[76:79], v166 offset:18528
	s_waitcnt lgkmcnt(0)
	s_barrier
	v_mfma_f32_32x32x16_bf16 v[48:63], v[76:79], v[68:71], v[48:63]
	v_mfma_f32_32x32x16_bf16 v[16:31], v[72:75], v[68:71], v[16:31]
	s_nop 10
	v_mul_f32_e32 v48, 0xbfb8aa3b, v48
	v_mul_f32_e32 v49, 0xbfb8aa3b, v49
	v_exp_f32_e32 v48, v48
	v_exp_f32_e32 v49, v49
	v_mul_f32_e32 v51, 0xbfb8aa3b, v51
	v_exp_f32_e32 v51, v51
	v_pk_add_f32 v[48:49], v[48:49], 1.0 op_sel_hi:[1,0]
	s_nop 0
	v_div_scale_f32 v68, s[12:13], v49, v49, 1.0
	v_rcp_f32_e32 v69, v68
	v_mfma_f32_32x32x16_bf16 v[0:15], v[72:75], v[64:67], v[0:15]
	v_mul_f32_e32 v16, 0xbfb8aa3b, v16
	v_mul_f32_e32 v17, 0xbfb8aa3b, v17
	v_fma_f32 v70, -v68, v69, 1.0
	v_fmac_f32_e32 v69, v70, v69
	v_div_scale_f32 v70, vcc, 1.0, v49, 1.0
	v_mul_f32_e32 v71, v70, v69
	v_fma_f32 v72, -v68, v71, v70
	v_fmac_f32_e32 v71, v72, v69
	v_fma_f32 v68, -v68, v71, v70
	v_div_fmas_f32 v68, v68, v69, v71
	v_div_fixup_f32 v49, v68, v49, 1.0
	v_mfma_f32_32x32x16_bf16 v[32:47], v[76:79], v[64:67], v[32:47]
	v_lshlrev_b32_e32 v64, 16, v223
	v_lshlrev_b32_e32 v66, 16, v200
	v_and_b32_e32 v65, 0xffff0000, v223
	v_and_b32_e32 v67, 0xffff0000, v200
	v_rcp_f32_e32 v48, v48
	s_nop 0
	v_pk_fma_f32 v[48:49], v[48:49], v[66:67], v[64:65]
	v_lshlrev_b32_e32 v64, 16, v189
	v_cvt_pk_bf16_f32 v223, v48, v49
	v_mul_f32_e32 v49, 0xbfb8aa3b, v50
	v_exp_f32_e32 v50, v49
	v_lshlrev_b32_e32 v48, 16, v222
	v_and_b32_e32 v49, 0xffff0000, v222
	v_and_b32_e32 v65, 0xffff0000, v189
	v_pk_add_f32 v[50:51], v[50:51], 1.0 op_sel_hi:[1,0]
	v_mul_f32_e32 v32, 0xbfb8aa3b, v32
	v_mul_f32_e32 v33, 0xbfb8aa3b, v33
	v_exp_f32_e32 v32, v32
	v_exp_f32_e32 v33, v33
	v_rcp_f32_e32 v51, v51
	s_nop 0
	v_pk_add_f32 v[32:33], v[32:33], 1.0 op_sel_hi:[1,0]
	v_mul_f32_e32 v35, 0xbfb8aa3b, v35
	v_exp_f32_e32 v35, v35
	v_rcp_f32_e32 v50, v50
	s_nop 0
	v_pk_fma_f32 v[48:49], v[50:51], v[64:65], v[48:49]
	v_mul_f32_e32 v51, 0xbfb8aa3b, v53
	v_cvt_pk_bf16_f32 v222, v48, v49
	v_mul_f32_e32 v49, 0xbfb8aa3b, v52
	v_exp_f32_e32 v50, v49
	v_exp_f32_e32 v51, v51
	v_lshlrev_b32_e32 v48, 16, v221
	v_lshlrev_b32_e32 v52, 16, v188
	v_and_b32_e32 v49, 0xffff0000, v221
	v_pk_add_f32 v[50:51], v[50:51], 1.0 op_sel_hi:[1,0]
	v_and_b32_e32 v53, 0xffff0000, v188
	v_exp_f32_e32 v16, v16
	v_exp_f32_e32 v17, v17
	v_mul_f32_e32 v19, 0xbfb8aa3b, v19
	v_rcp_f32_e32 v51, v51
	s_nop 0
	v_pk_add_f32 v[16:17], v[16:17], 1.0 op_sel_hi:[1,0]
	v_exp_f32_e32 v19, v19
	v_mul_f32_e32 v0, 0xbfb8aa3b, v0
	v_rcp_f32_e32 v50, v50
	s_nop 0
	v_pk_fma_f32 v[48:49], v[50:51], v[52:53], v[48:49]
	v_mul_f32_e32 v51, 0xbfb8aa3b, v55
	v_cvt_pk_bf16_f32 v221, v48, v49
	v_mul_f32_e32 v49, 0xbfb8aa3b, v54
	v_exp_f32_e32 v50, v49
	v_exp_f32_e32 v51, v51
	v_lshlrev_b32_e32 v48, 16, v220
	v_lshlrev_b32_e32 v52, 16, v208
	v_and_b32_e32 v49, 0xffff0000, v220
	v_pk_add_f32 v[50:51], v[50:51], 1.0 op_sel_hi:[1,0]
	v_and_b32_e32 v53, 0xffff0000, v208
	v_mul_f32_e32 v1, 0xbfb8aa3b, v1
	v_exp_f32_e32 v0, v0
	v_exp_f32_e32 v1, v1
	v_rcp_f32_e32 v51, v51
	s_nop 0
	v_pk_add_f32 v[0:1], v[0:1], 1.0 op_sel_hi:[1,0]
	v_mul_f32_e32 v3, 0xbfb8aa3b, v3
	v_exp_f32_e32 v3, v3
	v_rcp_f32_e32 v50, v50
	s_nop 0
	v_pk_fma_f32 v[48:49], v[50:51], v[52:53], v[48:49]
	v_mul_f32_e32 v51, 0xbfb8aa3b, v57
	v_cvt_pk_bf16_f32 v220, v48, v49
	v_mul_f32_e32 v49, 0xbfb8aa3b, v56
	v_exp_f32_e32 v50, v49
	v_exp_f32_e32 v51, v51
	v_lshlrev_b32_e32 v48, 16, v219
	v_lshlrev_b32_e32 v52, 16, v195
	v_and_b32_e32 v49, 0xffff0000, v219
	v_pk_add_f32 v[50:51], v[50:51], 1.0 op_sel_hi:[1,0]
	v_and_b32_e32 v53, 0xffff0000, v195
	v_rcp_f32_e32 v51, v51
	s_nop 0
	v_rcp_f32_e32 v50, v50
	s_nop 0
	v_pk_fma_f32 v[48:49], v[50:51], v[52:53], v[48:49]
	v_mul_f32_e32 v51, 0xbfb8aa3b, v59
	v_cvt_pk_bf16_f32 v219, v48, v49
	v_mul_f32_e32 v49, 0xbfb8aa3b, v58
	v_exp_f32_e32 v50, v49
	v_exp_f32_e32 v51, v51
	v_lshlrev_b32_e32 v48, 16, v218
	v_lshlrev_b32_e32 v52, 16, v192
	v_and_b32_e32 v49, 0xffff0000, v218
	v_pk_add_f32 v[50:51], v[50:51], 1.0 op_sel_hi:[1,0]
	v_and_b32_e32 v53, 0xffff0000, v192
	v_rcp_f32_e32 v51, v51
	s_nop 0
	v_rcp_f32_e32 v50, v50
	s_nop 0
	v_pk_fma_f32 v[48:49], v[50:51], v[52:53], v[48:49]
	v_mul_f32_e32 v51, 0xbfb8aa3b, v61
	v_cvt_pk_bf16_f32 v218, v48, v49
	v_mul_f32_e32 v49, 0xbfb8aa3b, v60
	v_exp_f32_e32 v50, v49
	v_exp_f32_e32 v51, v51
	v_lshlrev_b32_e32 v48, 16, v217
	v_lshlrev_b32_e32 v52, 16, v250
	v_and_b32_e32 v49, 0xffff0000, v217
	v_pk_add_f32 v[50:51], v[50:51], 1.0 op_sel_hi:[1,0]
	v_and_b32_e32 v53, 0xffff0000, v250
	v_rcp_f32_e32 v51, v51
	s_nop 0
	v_rcp_f32_e32 v50, v50
	s_nop 0
	v_pk_fma_f32 v[48:49], v[50:51], v[52:53], v[48:49]
	v_mul_f32_e32 v51, 0xbfb8aa3b, v63
	v_cvt_pk_bf16_f32 v217, v48, v49
	v_mul_f32_e32 v49, 0xbfb8aa3b, v62
	v_exp_f32_e32 v50, v49
	v_exp_f32_e32 v51, v51
	v_lshlrev_b32_e32 v48, 16, v216
	v_lshlrev_b32_e32 v52, 16, v249
	v_and_b32_e32 v49, 0xffff0000, v216
	v_pk_add_f32 v[50:51], v[50:51], 1.0 op_sel_hi:[1,0]
	v_and_b32_e32 v53, 0xffff0000, v249
	v_rcp_f32_e32 v51, v51
	s_nop 0
	v_rcp_f32_e32 v50, v50
	s_nop 0
	v_pk_fma_f32 v[48:49], v[50:51], v[52:53], v[48:49]
	v_cvt_pk_bf16_f32 v216, v48, v49
	v_lshlrev_b32_e32 v48, 16, v215
	v_lshlrev_b32_e32 v50, 16, v248
	v_rcp_f32_e32 v33, v33
	s_nop 0
	v_and_b32_e32 v49, 0xffff0000, v215
	v_and_b32_e32 v51, 0xffff0000, v248
	v_rcp_f32_e32 v32, v32
	s_nop 0
	v_pk_fma_f32 v[32:33], v[32:33], v[50:51], v[48:49]
	v_lshlrev_b32_e32 v48, 16, v247
	v_cvt_pk_bf16_f32 v215, v32, v33
	v_mul_f32_e32 v33, 0xbfb8aa3b, v34
	v_exp_f32_e32 v34, v33
	v_lshlrev_b32_e32 v32, 16, v214
	v_and_b32_e32 v33, 0xffff0000, v214
	v_and_b32_e32 v49, 0xffff0000, v247
	v_pk_add_f32 v[34:35], v[34:35], 1.0 op_sel_hi:[1,0]
	s_nop 0
	v_rcp_f32_e32 v35, v35
	s_nop 0
	v_rcp_f32_e32 v34, v34
	s_nop 0
	v_pk_fma_f32 v[32:33], v[34:35], v[48:49], v[32:33]
	v_mul_f32_e32 v35, 0xbfb8aa3b, v37
	v_cvt_pk_bf16_f32 v214, v32, v33
	v_mul_f32_e32 v33, 0xbfb8aa3b, v36
	v_exp_f32_e32 v34, v33
	v_exp_f32_e32 v35, v35
	v_lshlrev_b32_e32 v32, 16, v213
	v_lshlrev_b32_e32 v36, 16, v246
	v_and_b32_e32 v33, 0xffff0000, v213
	v_pk_add_f32 v[34:35], v[34:35], 1.0 op_sel_hi:[1,0]
	v_and_b32_e32 v37, 0xffff0000, v246
	v_rcp_f32_e32 v35, v35
	s_nop 0
	v_rcp_f32_e32 v34, v34
	s_nop 0
	v_pk_fma_f32 v[32:33], v[34:35], v[36:37], v[32:33]
	v_mul_f32_e32 v35, 0xbfb8aa3b, v39
	v_cvt_pk_bf16_f32 v213, v32, v33
	v_mul_f32_e32 v33, 0xbfb8aa3b, v38
	v_exp_f32_e32 v34, v33
	v_exp_f32_e32 v35, v35
	v_lshlrev_b32_e32 v32, 16, v212
	v_lshlrev_b32_e32 v36, 16, v245
	v_and_b32_e32 v33, 0xffff0000, v212
	v_pk_add_f32 v[34:35], v[34:35], 1.0 op_sel_hi:[1,0]
	v_and_b32_e32 v37, 0xffff0000, v245
	v_rcp_f32_e32 v35, v35
	s_nop 0
	v_rcp_f32_e32 v34, v34
	s_nop 0
	v_pk_fma_f32 v[32:33], v[34:35], v[36:37], v[32:33]
	v_mul_f32_e32 v35, 0xbfb8aa3b, v41
	v_cvt_pk_bf16_f32 v212, v32, v33
	v_mul_f32_e32 v33, 0xbfb8aa3b, v40
	v_exp_f32_e32 v34, v33
	v_exp_f32_e32 v35, v35
	v_lshlrev_b32_e32 v32, 16, v211
	v_lshlrev_b32_e32 v36, 16, v244
	v_and_b32_e32 v33, 0xffff0000, v211
	v_pk_add_f32 v[34:35], v[34:35], 1.0 op_sel_hi:[1,0]
	v_and_b32_e32 v37, 0xffff0000, v244
	v_rcp_f32_e32 v35, v35
	s_nop 0
	v_rcp_f32_e32 v34, v34
	s_nop 0
	v_pk_fma_f32 v[32:33], v[34:35], v[36:37], v[32:33]
	v_mul_f32_e32 v35, 0xbfb8aa3b, v43
	v_cvt_pk_bf16_f32 v211, v32, v33
	v_mul_f32_e32 v33, 0xbfb8aa3b, v42
	v_exp_f32_e32 v34, v33
	v_exp_f32_e32 v35, v35
	v_lshlrev_b32_e32 v32, 16, v210
	v_lshlrev_b32_e32 v36, 16, v243
	v_and_b32_e32 v33, 0xffff0000, v210
	v_pk_add_f32 v[34:35], v[34:35], 1.0 op_sel_hi:[1,0]
	v_and_b32_e32 v37, 0xffff0000, v243
	v_rcp_f32_e32 v35, v35
	s_nop 0
	v_rcp_f32_e32 v34, v34
	s_nop 0
	v_pk_fma_f32 v[32:33], v[34:35], v[36:37], v[32:33]
	v_mul_f32_e32 v35, 0xbfb8aa3b, v45
	v_cvt_pk_bf16_f32 v210, v32, v33
	v_mul_f32_e32 v33, 0xbfb8aa3b, v44
	v_exp_f32_e32 v34, v33
	v_exp_f32_e32 v35, v35
	v_lshlrev_b32_e32 v32, 16, v185
	v_lshlrev_b32_e32 v36, 16, v242
	v_and_b32_e32 v33, 0xffff0000, v185
	v_pk_add_f32 v[34:35], v[34:35], 1.0 op_sel_hi:[1,0]
	v_and_b32_e32 v37, 0xffff0000, v242
	v_rcp_f32_e32 v35, v35
	s_nop 0
	v_rcp_f32_e32 v34, v34
	s_nop 0
	v_pk_fma_f32 v[32:33], v[34:35], v[36:37], v[32:33]
	v_mul_f32_e32 v35, 0xbfb8aa3b, v47
	v_cvt_pk_bf16_f32 v185, v32, v33
	v_mul_f32_e32 v33, 0xbfb8aa3b, v46
	v_exp_f32_e32 v34, v33
	v_exp_f32_e32 v35, v35
	v_lshlrev_b32_e32 v32, 16, v184
	v_lshlrev_b32_e32 v36, 16, v241
	v_and_b32_e32 v33, 0xffff0000, v184
	v_pk_add_f32 v[34:35], v[34:35], 1.0 op_sel_hi:[1,0]
	v_and_b32_e32 v37, 0xffff0000, v241
	v_rcp_f32_e32 v35, v35
	s_nop 0
	v_rcp_f32_e32 v34, v34
	s_nop 0
	v_pk_fma_f32 v[32:33], v[34:35], v[36:37], v[32:33]
	v_cvt_pk_bf16_f32 v184, v32, v33
	v_lshlrev_b32_e32 v32, 16, v183
	v_lshlrev_b32_e32 v34, 16, v240
	v_rcp_f32_e32 v17, v17
	s_nop 0
	v_and_b32_e32 v33, 0xffff0000, v183
	v_and_b32_e32 v35, 0xffff0000, v240
	v_rcp_f32_e32 v16, v16
	s_nop 0
	v_pk_fma_f32 v[16:17], v[16:17], v[34:35], v[32:33]
	v_lshlrev_b32_e32 v32, 16, v239
	v_cvt_pk_bf16_f32 v183, v16, v17
	v_mul_f32_e32 v17, 0xbfb8aa3b, v18
	v_exp_f32_e32 v18, v17
	v_lshlrev_b32_e32 v16, 16, v182
	v_and_b32_e32 v17, 0xffff0000, v182
	v_and_b32_e32 v33, 0xffff0000, v239
	v_pk_add_f32 v[18:19], v[18:19], 1.0 op_sel_hi:[1,0]
	s_nop 0
	v_rcp_f32_e32 v19, v19
	s_nop 0
	v_rcp_f32_e32 v18, v18
	s_nop 0
	v_pk_fma_f32 v[16:17], v[18:19], v[32:33], v[16:17]
	v_mul_f32_e32 v19, 0xbfb8aa3b, v21
	v_cvt_pk_bf16_f32 v182, v16, v17
	v_mul_f32_e32 v17, 0xbfb8aa3b, v20
	v_exp_f32_e32 v18, v17
	v_exp_f32_e32 v19, v19
	v_lshlrev_b32_e32 v16, 16, v181
	v_lshlrev_b32_e32 v20, 16, v238
	v_and_b32_e32 v17, 0xffff0000, v181
	v_pk_add_f32 v[18:19], v[18:19], 1.0 op_sel_hi:[1,0]
	v_and_b32_e32 v21, 0xffff0000, v238
	v_rcp_f32_e32 v19, v19
	s_nop 0
	v_rcp_f32_e32 v18, v18
	s_nop 0
	v_pk_fma_f32 v[16:17], v[18:19], v[20:21], v[16:17]
	v_mul_f32_e32 v19, 0xbfb8aa3b, v23
	v_cvt_pk_bf16_f32 v181, v16, v17
	v_mul_f32_e32 v17, 0xbfb8aa3b, v22
	v_exp_f32_e32 v18, v17
	v_exp_f32_e32 v19, v19
	v_lshlrev_b32_e32 v16, 16, v180
	v_lshlrev_b32_e32 v20, 16, v237
	v_and_b32_e32 v17, 0xffff0000, v180
	v_pk_add_f32 v[18:19], v[18:19], 1.0 op_sel_hi:[1,0]
	v_and_b32_e32 v21, 0xffff0000, v237
	v_rcp_f32_e32 v19, v19
	s_nop 0
	v_rcp_f32_e32 v18, v18
	s_nop 0
	v_pk_fma_f32 v[16:17], v[18:19], v[20:21], v[16:17]
	v_mul_f32_e32 v19, 0xbfb8aa3b, v25
	v_cvt_pk_bf16_f32 v180, v16, v17
	v_mul_f32_e32 v17, 0xbfb8aa3b, v24
	v_exp_f32_e32 v18, v17
	v_exp_f32_e32 v19, v19
	v_lshlrev_b32_e32 v16, 16, v179
	v_lshlrev_b32_e32 v20, 16, v236
	v_and_b32_e32 v17, 0xffff0000, v179
	v_pk_add_f32 v[18:19], v[18:19], 1.0 op_sel_hi:[1,0]
	v_and_b32_e32 v21, 0xffff0000, v236
	v_rcp_f32_e32 v19, v19
	s_nop 0
	v_rcp_f32_e32 v18, v18
	s_nop 0
	v_pk_fma_f32 v[16:17], v[18:19], v[20:21], v[16:17]
	v_mul_f32_e32 v19, 0xbfb8aa3b, v27
	v_cvt_pk_bf16_f32 v179, v16, v17
	v_mul_f32_e32 v17, 0xbfb8aa3b, v26
	v_exp_f32_e32 v18, v17
	v_exp_f32_e32 v19, v19
	v_lshlrev_b32_e32 v16, 16, v178
	v_lshlrev_b32_e32 v20, 16, v235
	v_and_b32_e32 v17, 0xffff0000, v178
	v_pk_add_f32 v[18:19], v[18:19], 1.0 op_sel_hi:[1,0]
	v_and_b32_e32 v21, 0xffff0000, v235
	v_rcp_f32_e32 v19, v19
	s_nop 0
	v_rcp_f32_e32 v18, v18
	s_nop 0
	v_pk_fma_f32 v[16:17], v[18:19], v[20:21], v[16:17]
	v_mul_f32_e32 v19, 0xbfb8aa3b, v29
	v_cvt_pk_bf16_f32 v178, v16, v17
	v_mul_f32_e32 v17, 0xbfb8aa3b, v28
	v_exp_f32_e32 v18, v17
	v_exp_f32_e32 v19, v19
	v_lshlrev_b32_e32 v16, 16, v177
	v_lshlrev_b32_e32 v20, 16, v234
	v_and_b32_e32 v17, 0xffff0000, v177
	v_pk_add_f32 v[18:19], v[18:19], 1.0 op_sel_hi:[1,0]
	v_and_b32_e32 v21, 0xffff0000, v234
	v_rcp_f32_e32 v19, v19
	s_nop 0
	v_rcp_f32_e32 v18, v18
	s_nop 0
	v_pk_fma_f32 v[16:17], v[18:19], v[20:21], v[16:17]
	v_mul_f32_e32 v19, 0xbfb8aa3b, v31
	v_cvt_pk_bf16_f32 v177, v16, v17
	v_mul_f32_e32 v17, 0xbfb8aa3b, v30
	v_exp_f32_e32 v18, v17
	v_exp_f32_e32 v19, v19
	v_lshlrev_b32_e32 v16, 16, v176
	v_lshlrev_b32_e32 v20, 16, v233
	v_and_b32_e32 v17, 0xffff0000, v176
	v_pk_add_f32 v[18:19], v[18:19], 1.0 op_sel_hi:[1,0]
	v_and_b32_e32 v21, 0xffff0000, v233
	v_rcp_f32_e32 v19, v19
	s_nop 0
	v_rcp_f32_e32 v18, v18
	s_nop 0
	v_pk_fma_f32 v[16:17], v[18:19], v[20:21], v[16:17]
	v_cvt_pk_bf16_f32 v176, v16, v17
	v_lshlrev_b32_e32 v16, 16, v175
	v_lshlrev_b32_e32 v18, 16, v232
	v_rcp_f32_e32 v1, v1
	s_nop 0
	v_and_b32_e32 v17, 0xffff0000, v175
	v_and_b32_e32 v19, 0xffff0000, v232
	v_rcp_f32_e32 v0, v0
	s_nop 0
	v_pk_fma_f32 v[0:1], v[0:1], v[18:19], v[16:17]
	v_lshlrev_b32_e32 v16, 16, v231
	v_cvt_pk_bf16_f32 v175, v0, v1
	v_mul_f32_e32 v1, 0xbfb8aa3b, v2
	v_exp_f32_e32 v2, v1
	v_lshlrev_b32_e32 v0, 16, v174
	v_and_b32_e32 v1, 0xffff0000, v174
	v_and_b32_e32 v17, 0xffff0000, v231
	v_pk_add_f32 v[2:3], v[2:3], 1.0 op_sel_hi:[1,0]
	s_nop 0
	v_rcp_f32_e32 v3, v3
	s_nop 0
	v_rcp_f32_e32 v2, v2
	s_nop 0
	v_pk_fma_f32 v[0:1], v[2:3], v[16:17], v[0:1]
	v_mul_f32_e32 v3, 0xbfb8aa3b, v5
	v_cvt_pk_bf16_f32 v174, v0, v1
	v_mul_f32_e32 v1, 0xbfb8aa3b, v4
	v_exp_f32_e32 v2, v1
	v_exp_f32_e32 v3, v3
	v_lshlrev_b32_e32 v0, 16, v173
	v_lshlrev_b32_e32 v4, 16, v230
	v_and_b32_e32 v1, 0xffff0000, v173
	v_pk_add_f32 v[2:3], v[2:3], 1.0 op_sel_hi:[1,0]
	v_and_b32_e32 v5, 0xffff0000, v230
	v_rcp_f32_e32 v3, v3
	s_nop 0
	v_rcp_f32_e32 v2, v2
	s_nop 0
	v_pk_fma_f32 v[0:1], v[2:3], v[4:5], v[0:1]
	v_mul_f32_e32 v3, 0xbfb8aa3b, v7
	v_cvt_pk_bf16_f32 v173, v0, v1
	v_mul_f32_e32 v1, 0xbfb8aa3b, v6
	v_exp_f32_e32 v2, v1
	v_exp_f32_e32 v3, v3
	v_lshlrev_b32_e32 v0, 16, v172
	v_lshlrev_b32_e32 v4, 16, v229
	v_and_b32_e32 v1, 0xffff0000, v172
	v_pk_add_f32 v[2:3], v[2:3], 1.0 op_sel_hi:[1,0]
	v_and_b32_e32 v5, 0xffff0000, v229
	v_rcp_f32_e32 v3, v3
	s_nop 0
	v_rcp_f32_e32 v2, v2
	s_nop 0
	v_pk_fma_f32 v[0:1], v[2:3], v[4:5], v[0:1]
	v_mul_f32_e32 v3, 0xbfb8aa3b, v9
	v_cvt_pk_bf16_f32 v172, v0, v1
	v_mul_f32_e32 v1, 0xbfb8aa3b, v8
	v_exp_f32_e32 v2, v1
	v_exp_f32_e32 v3, v3
	v_lshlrev_b32_e32 v0, 16, v171
	v_lshlrev_b32_e32 v4, 16, v228
	v_and_b32_e32 v1, 0xffff0000, v171
	v_pk_add_f32 v[2:3], v[2:3], 1.0 op_sel_hi:[1,0]
	v_and_b32_e32 v5, 0xffff0000, v228
	v_rcp_f32_e32 v3, v3
	s_nop 0
	v_rcp_f32_e32 v2, v2
	s_nop 0
	v_pk_fma_f32 v[0:1], v[2:3], v[4:5], v[0:1]
	v_mul_f32_e32 v3, 0xbfb8aa3b, v11
	v_cvt_pk_bf16_f32 v171, v0, v1
	v_mul_f32_e32 v1, 0xbfb8aa3b, v10
	v_exp_f32_e32 v2, v1
	v_exp_f32_e32 v3, v3
	v_lshlrev_b32_e32 v0, 16, v170
	v_lshlrev_b32_e32 v4, 16, v227
	v_and_b32_e32 v1, 0xffff0000, v170
	v_pk_add_f32 v[2:3], v[2:3], 1.0 op_sel_hi:[1,0]
	v_and_b32_e32 v5, 0xffff0000, v227
	v_rcp_f32_e32 v3, v3
	s_nop 0
	v_rcp_f32_e32 v2, v2
	s_nop 0
	v_pk_fma_f32 v[0:1], v[2:3], v[4:5], v[0:1]
	v_mul_f32_e32 v3, 0xbfb8aa3b, v13
	v_cvt_pk_bf16_f32 v170, v0, v1
	v_mul_f32_e32 v1, 0xbfb8aa3b, v12
	v_exp_f32_e32 v2, v1
	v_exp_f32_e32 v3, v3
	v_lshlrev_b32_e32 v0, 16, v169
	v_lshlrev_b32_e32 v4, 16, v226
	v_and_b32_e32 v1, 0xffff0000, v169
	v_pk_add_f32 v[2:3], v[2:3], 1.0 op_sel_hi:[1,0]
	v_and_b32_e32 v5, 0xffff0000, v226
	v_rcp_f32_e32 v3, v3
	s_nop 0
	v_rcp_f32_e32 v2, v2
	s_nop 0
	v_pk_fma_f32 v[0:1], v[2:3], v[4:5], v[0:1]
	v_mul_f32_e32 v3, 0xbfb8aa3b, v15
	v_cvt_pk_bf16_f32 v169, v0, v1
	v_mul_f32_e32 v1, 0xbfb8aa3b, v14
	v_exp_f32_e32 v4, v1
	v_exp_f32_e32 v5, v3
	v_lshlrev_b32_e32 v0, 16, v224
	v_lshlrev_b32_e32 v2, 16, v225
	v_and_b32_e32 v1, 0xffff0000, v224
	v_pk_add_f32 v[4:5], v[4:5], 1.0 op_sel_hi:[1,0]
	v_and_b32_e32 v3, 0xffff0000, v225
	v_rcp_f32_e32 v5, v5
	s_nop 0
	v_rcp_f32_e32 v4, v4
	s_nop 0
	v_pk_fma_f32 v[0:1], v[4:5], v[2:3], v[0:1]
	s_nop 0
	v_cvt_pk_bf16_f32 v224, v0, v1
	s_cbranch_scc0 .LBB0_2087
	v_readfirstlane_b32 s20, v186
	v_and_b32_e32 v0, 63, v186
	v_and_b32_e32 v1, 31, v0
	v_lshrrev_b32_e32 v2, 5, v0
	s_lshr_b32 s20, s20, 6
	s_and_b32 s21, s20, 1
	s_lshr_b32 s22, s20, 1
	s_mul_i32 s20, s20, 0x2400
	v_mul_u32_u24_e32 v3, 0x240, v2
	v_lshl_add_u32 v3, v1, 1, v3
	v_add_u32_e32 v3, s20, v3
	v_lshrrev_b32_e32 v4, 3, v0
	v_and_b32_e32 v5, 7, v0
	v_mul_u32_u24_e32 v6, 0x90, v4
	v_lshl_add_u32 v6, v5, 4, v6
	v_add_u32_e32 v6, s20, v6
	s_lshl_b32 s22, s22, 6
	s_add_i32 s22, s22, s4
	v_add_u32_e32 v7, s22, v4
	v_lshlrev_b32_e32 v7, 11, v7
	s_lshl_b32 s21, s21, 6
	s_add_i32 s21, s21, s6
	s_lshl_b32 s21, s21, 1
	v_add_u32_e32 v7, s21, v7
	v_lshl_add_u32 v7, v5, 4, v7
	s_add_u32 s22, s88, 0x9a00000
	s_addc_u32 s23, s89, 0
	ds_write_b16 v3, v223
	ds_write_b16_d16_hi v3, v223 offset:144
	ds_write_b16 v3, v222 offset:288
	ds_write_b16_d16_hi v3, v222 offset:432
	ds_write_b16 v3, v221 offset:1152
	ds_write_b16_d16_hi v3, v221 offset:1296
	ds_write_b16 v3, v220 offset:1440
	ds_write_b16_d16_hi v3, v220 offset:1584
	ds_write_b16 v3, v219 offset:2304
	ds_write_b16_d16_hi v3, v219 offset:2448
	ds_write_b16 v3, v218 offset:2592
	ds_write_b16_d16_hi v3, v218 offset:2736
	ds_write_b16 v3, v217 offset:3456
	ds_write_b16_d16_hi v3, v217 offset:3600
	ds_write_b16 v3, v216 offset:3744
	ds_write_b16_d16_hi v3, v216 offset:3888
	ds_write_b16 v3, v215 offset:64
	ds_write_b16_d16_hi v3, v215 offset:208
	ds_write_b16 v3, v214 offset:352
	ds_write_b16_d16_hi v3, v214 offset:496
	ds_write_b16 v3, v213 offset:1216
	ds_write_b16_d16_hi v3, v213 offset:1360
	ds_write_b16 v3, v212 offset:1504
	ds_write_b16_d16_hi v3, v212 offset:1648
	ds_write_b16 v3, v211 offset:2368
	ds_write_b16_d16_hi v3, v211 offset:2512
	ds_write_b16 v3, v210 offset:2656
	ds_write_b16_d16_hi v3, v210 offset:2800
	ds_write_b16 v3, v185 offset:3520
	ds_write_b16_d16_hi v3, v185 offset:3664
	ds_write_b16 v3, v184 offset:3808
	ds_write_b16_d16_hi v3, v184 offset:3952
	ds_write_b16 v3, v183 offset:4608
	ds_write_b16_d16_hi v3, v183 offset:4752
	ds_write_b16 v3, v182 offset:4896
	ds_write_b16_d16_hi v3, v182 offset:5040
	ds_write_b16 v3, v181 offset:5760
	ds_write_b16_d16_hi v3, v181 offset:5904
	ds_write_b16 v3, v180 offset:6048
	ds_write_b16_d16_hi v3, v180 offset:6192
	ds_write_b16 v3, v179 offset:6912
	ds_write_b16_d16_hi v3, v179 offset:7056
	ds_write_b16 v3, v178 offset:7200
	ds_write_b16_d16_hi v3, v178 offset:7344
	ds_write_b16 v3, v177 offset:8064
	ds_write_b16_d16_hi v3, v177 offset:8208
	ds_write_b16 v3, v176 offset:8352
	ds_write_b16_d16_hi v3, v176 offset:8496
	ds_write_b16 v3, v175 offset:4672
	ds_write_b16_d16_hi v3, v175 offset:4816
	ds_write_b16 v3, v174 offset:4960
	ds_write_b16_d16_hi v3, v174 offset:5104
	ds_write_b16 v3, v173 offset:5824
	ds_write_b16_d16_hi v3, v173 offset:5968
	ds_write_b16 v3, v172 offset:6112
	ds_write_b16_d16_hi v3, v172 offset:6256
	ds_write_b16 v3, v171 offset:6976
	ds_write_b16_d16_hi v3, v171 offset:7120
	ds_write_b16 v3, v170 offset:7264
	ds_write_b16_d16_hi v3, v170 offset:7408
	ds_write_b16 v3, v169 offset:8128
	ds_write_b16_d16_hi v3, v169 offset:8272
	ds_write_b16 v3, v224 offset:8416
	ds_write_b16_d16_hi v3, v224 offset:8560
	s_waitcnt lgkmcnt(0)
	ds_read_b128 v[16:19], v6
	ds_read_b128 v[20:23], v6 offset:1152
	ds_read_b128 v[24:27], v6 offset:2304
	ds_read_b128 v[28:31], v6 offset:3456
	ds_read_b128 v[32:35], v6 offset:4608
	ds_read_b128 v[36:39], v6 offset:5760
	ds_read_b128 v[40:43], v6 offset:6912
	ds_read_b128 v[44:47], v6 offset:8064
	s_waitcnt lgkmcnt(7)
	global_store_dwordx4 v7, v[16:19], s[22:23]
	v_add_u32_e32 v7, 0x4000, v7
	s_waitcnt lgkmcnt(6)
	global_store_dwordx4 v7, v[20:23], s[22:23]
	v_add_u32_e32 v7, 0x4000, v7
	s_waitcnt lgkmcnt(5)
	global_store_dwordx4 v7, v[24:27], s[22:23]
	v_add_u32_e32 v7, 0x4000, v7
	s_waitcnt lgkmcnt(4)
	global_store_dwordx4 v7, v[28:31], s[22:23]
	v_add_u32_e32 v7, 0x4000, v7
	s_waitcnt lgkmcnt(3)
	global_store_dwordx4 v7, v[32:35], s[22:23]
	v_add_u32_e32 v7, 0x4000, v7
	s_waitcnt lgkmcnt(2)
	global_store_dwordx4 v7, v[36:39], s[22:23]
	v_add_u32_e32 v7, 0x4000, v7
	s_waitcnt lgkmcnt(1)
	global_store_dwordx4 v7, v[40:43], s[22:23]
	v_add_u32_e32 v7, 0x4000, v7
	s_waitcnt lgkmcnt(0)
	global_store_dwordx4 v7, v[44:47], s[22:23]
	v_readlane_b32 s4, v252, 22
	s_nop 3
	s_add_i32 s18, s18, s4
	s_cmp_ge_i32 s18, s24
	s_cbranch_scc0 .LBB0_2078
